# cache policy: P1 epilogue stores sc0 sc1 nt; P0 x-row loads and weight-transpose loads nt
# speedup vs baseline: 1.0409x; 1.0098x over previous
; #define LDS_WAIT() asm volatile("s_waitcnt lgkmcnt(0)" ::: "memory")
; __device__ __forceinline__ void transpose_item(const float* W, int ldw, int nblk, bf16* WT, int ldt, LAS float* scr, int item, int lane) {
;     const int kb = item / nblk, nb = item % nblk, k0 = 64 * kb, n0 = 32 * nb;
; #pragma unroll 8
;     for (int i = 0; i < 32; ++i) { const int kk = 2 * i + (lane >> 5); scr[kk * 33 + (lane & 31)] = W[(size_t)(k0 + kk) * ldw + n0 + (lane & 31)]; }
;     LDS_WAIT(); asm volatile("" ::: "memory");
.LBB0_21:
	s_lshl_b32 s12, s0, 1
	s_lshl_b32 s13, s5, 1
	v_or_b32_e32 v4, s13, v30
	s_add_i32 s14, s12, 4
	s_add_i32 s15, s13, 4
	v_mov_b32_e32 v41, v5
	s_add_i32 s17, s13, 8
	v_lshlrev_b64 v[54:55], 12, v[4:5]
	v_or_b32_e32 v40, s14, v3
	v_or_b32_e32 v4, s15, v30
	v_mov_b32_e32 v39, v5
	v_or_b32_e32 v38, s12, v3
	s_add_i32 s19, s13, 12
	v_lshlrev_b64 v[40:41], 12, v[40:41]
	v_lshlrev_b64 v[56:57], 12, v[4:5]
	v_or_b32_e32 v4, s17, v30
	s_add_i32 s16, s12, 8
	s_add_i32 s18, s12, 12
	s_add_i32 s35, s13, 16
	v_lshlrev_b64 v[38:39], 12, v[38:39]
	v_lshl_add_u64 v[54:55], v[28:29], 0, v[54:55]
	v_lshl_add_u64 v[40:41], v[28:29], 0, v[40:41]
	v_lshlrev_b64 v[58:59], 12, v[4:5]
	v_or_b32_e32 v4, s19, v30
	v_mov_b32_e32 v43, v5
	v_mov_b32_e32 v45, v5
	s_add_i32 s41, s13, 20
	v_or_b32_e32 v42, s16, v3
	v_or_b32_e32 v44, s18, v3
	v_lshl_add_u64 v[38:39], v[28:29], 0, v[38:39]
	v_lshl_add_u64 v[56:57], v[28:29], 0, v[56:57]
	global_load_dword v37, v[54:55], off nt
	global_load_dword v70, v[38:39], off nt
	global_load_dword v71, v[56:57], off nt
	global_load_dword v72, v[40:41], off nt
	v_lshlrev_b64 v[40:41], 12, v[4:5]
	v_or_b32_e32 v4, s35, v30
	s_add_i32 s33, s12, 16
	s_add_i32 s40, s12, 20
	s_add_i32 s55, s13, 24
	v_lshlrev_b64 v[42:43], 12, v[42:43]
	v_lshlrev_b64 v[44:45], 12, v[44:45]
	v_lshl_add_u64 v[38:39], v[28:29], 0, v[58:59]
	v_lshl_add_u64 v[40:41], v[28:29], 0, v[40:41]
	v_lshlrev_b64 v[54:55], 12, v[4:5]
	v_or_b32_e32 v4, s41, v30
	v_mov_b32_e32 v47, v5
	v_mov_b32_e32 v49, v5
	s_add_i32 s54, s12, 24
	s_add_i32 s56, s12, 28
	s_add_i32 s57, s13, 28
	v_or_b32_e32 v46, s33, v3
	v_or_b32_e32 v48, s40, v3
	v_lshl_add_u64 v[42:43], v[28:29], 0, v[42:43]
	v_lshl_add_u64 v[44:45], v[28:29], 0, v[44:45]
	global_load_dword v73, v[38:39], off nt
	global_load_dword v74, v[42:43], off nt
	global_load_dword v75, v[40:41], off nt
	global_load_dword v76, v[44:45], off nt
	v_lshlrev_b64 v[40:41], 12, v[4:5]
	v_or_b32_e32 v4, s55, v30
	v_mov_b32_e32 v51, v5
	v_mov_b32_e32 v53, v5
	v_or_b32_e32 v50, s54, v3
	v_or_b32_e32 v52, s56, v3
	v_lshlrev_b64 v[46:47], 12, v[46:47]
	v_lshlrev_b64 v[48:49], 12, v[48:49]
	v_lshl_add_u64 v[38:39], v[28:29], 0, v[54:55]
	v_lshl_add_u64 v[40:41], v[28:29], 0, v[40:41]
	v_lshlrev_b64 v[42:43], 12, v[4:5]
	v_or_b32_e32 v4, s57, v30
	v_lshlrev_b64 v[50:51], 12, v[50:51]
	v_lshlrev_b64 v[52:53], 12, v[52:53]
	v_lshl_add_u64 v[46:47], v[28:29], 0, v[46:47]
	v_lshl_add_u64 v[48:49], v[28:29], 0, v[48:49]
	global_load_dword v77, v[38:39], off nt
	global_load_dword v78, v[46:47], off nt
	global_load_dword v79, v[40:41], off nt
	global_load_dword v80, v[48:49], off nt
	v_lshl_add_u64 v[38:39], v[28:29], 0, v[42:43]
	v_lshlrev_b64 v[40:41], 12, v[4:5]
	v_lshl_add_u64 v[50:51], v[28:29], 0, v[50:51]
	v_lshl_add_u64 v[52:53], v[28:29], 0, v[52:53]
	v_lshl_add_u64 v[40:41], v[28:29], 0, v[40:41]
	global_load_dword v4, v[38:39], off nt
	global_load_dword v81, v[50:51], off nt
	global_load_dword v82, v[40:41], off nt
	global_load_dword v83, v[52:53], off nt
	v_or_b32_e32 v40, s12, v1
	v_or_b32_e32 v38, s13, v2
	s_add_i32 s5, s5, 16
	s_add_i32 s0, s0, 16
	s_add_i32 s11, s11, -16
	v_mad_u64_u32 v[38:39], s[12:13], v38, s8, v[8:9]
	v_mad_u64_u32 v[40:41], s[12:13], v40, s8, v[8:9]
	v_or_b32_e32 v39, s14, v1
	v_or_b32_e32 v41, s15, v2
	v_or_b32_e32 v48, s16, v1
	v_or_b32_e32 v46, s17, v2
	v_or_b32_e32 v52, s18, v1
	v_or_b32_e32 v50, s19, v2
	v_or_b32_e32 v56, s33, v1
	v_or_b32_e32 v54, s35, v2
	v_or_b32_e32 v60, s40, v1
	v_or_b32_e32 v58, s41, v2
	v_or_b32_e32 v64, s54, v1
	v_or_b32_e32 v62, s55, v2
	v_or_b32_e32 v68, s56, v1
	v_or_b32_e32 v66, s57, v2
	s_cmp_lg_u32 s11, 0
	v_mad_u64_u32 v[42:43], s[12:13], v41, s8, v[8:9]
	v_mad_u64_u32 v[44:45], s[12:13], v39, s8, v[8:9]
	v_mad_u64_u32 v[46:47], s[12:13], v46, s8, v[8:9]
	v_mad_u64_u32 v[48:49], s[12:13], v48, s8, v[8:9]
	v_mad_u64_u32 v[50:51], s[12:13], v50, s8, v[8:9]
	v_mad_u64_u32 v[52:53], s[12:13], v52, s8, v[8:9]
	v_mad_u64_u32 v[54:55], s[12:13], v54, s8, v[8:9]
	v_mad_u64_u32 v[56:57], s[12:13], v56, s8, v[8:9]
	v_mad_u64_u32 v[58:59], s[12:13], v58, s8, v[8:9]
	v_mad_u64_u32 v[60:61], s[12:13], v60, s8, v[8:9]
	v_mad_u64_u32 v[62:63], s[12:13], v62, s8, v[8:9]
	v_mad_u64_u32 v[64:65], s[12:13], v64, s8, v[8:9]
	v_mad_u64_u32 v[66:67], s[12:13], v66, s8, v[8:9]
	v_mad_u64_u32 v[68:69], s[12:13], v68, s8, v[8:9]
	s_waitcnt vmcnt(15)
	ds_write_b32 v38, v37
	s_waitcnt vmcnt(14)
	ds_write_b32 v40, v70
	s_waitcnt vmcnt(13)
	ds_write_b32 v42, v71
	s_waitcnt vmcnt(12)
	ds_write_b32 v44, v72
	s_waitcnt vmcnt(11)
	ds_write_b32 v46, v73
	s_waitcnt vmcnt(10)
	ds_write_b32 v48, v74
	s_waitcnt vmcnt(9)
	ds_write_b32 v50, v75
	s_waitcnt vmcnt(8)
	ds_write_b32 v52, v76
	s_waitcnt vmcnt(7)
	ds_write_b32 v54, v77
	s_waitcnt vmcnt(6)
	ds_write_b32 v56, v78
	s_waitcnt vmcnt(5)
	ds_write_b32 v58, v79
	s_waitcnt vmcnt(4)
	ds_write_b32 v60, v80
	s_waitcnt vmcnt(3)
	ds_write_b32 v62, v4
	s_waitcnt vmcnt(2)
	ds_write_b32 v64, v81
	s_waitcnt vmcnt(1)
	ds_write_b32 v66, v82
	s_waitcnt vmcnt(0)
	ds_write_b32 v68, v83
	s_cbranch_scc1 .LBB0_21
; #define GAS __attribute__((address_space(1)))
; #define LAS __attribute__((address_space(3)))
; #define LDS_WAIT() asm volatile("s_waitcnt lgkmcnt(0)" ::: "memory")
; __device__ __forceinline__ unsigned pk2(float lo, float hi) { return pg8::cvt_pk_bf16_c(lo, hi); }
; __device__ __forceinline__ void transpose_item(const float* W, int ldw, int nblk, bf16* WT, int ldt, LAS float* scr, int item, int lane) {
;     ...
;     const int c = lane & 7;
; #pragma unroll
;     for (int j = 0; j < 4; ++j) { const int n = (lane >> 3) + 8 * j; const LAS float* s = scr + (8 * c) * 33 + n;
;         v4u o; o.x = pk2(s[0 * 33], s[1 * 33]); o.y = pk2(s[2 * 33], s[3 * 33]); o.z = pk2(s[4 * 33], s[5 * 33]); o.w = pk2(s[6 * 33], s[7 * 33]);
;         *(GAS v4u*)(WT + (size_t)(n0 + n) * ldt + k0 + 8 * c) = o; }
;     LDS_WAIT(); asm volatile("" ::: "memory");
	s_waitcnt lgkmcnt(0)
	ds_read2_b32 v[28:29], v32 offset0:33 offset1:41
	ds_read2_b32 v[42:43], v32 offset1:8
	ds_read2_b32 v[44:45], v32 offset0:66 offset1:74
	ds_read2_b32 v[46:47], v32 offset0:99 offset1:107
	ds_read2_b32 v[48:49], v32 offset0:132 offset1:140
	ds_read2_b32 v[50:51], v32 offset0:165 offset1:173
	ds_read2_b32 v[52:53], v32 offset0:198 offset1:206
	ds_read2_b32 v[54:55], v32 offset0:231 offset1:239
	s_lshl_b32 s0, s4, 1
	v_or_b32_e32 v3, s6, v31
	v_lshl_add_u64 v[56:57], v[10:11], 0, s[0:1]
	v_lshlrev_b32_e32 v4, 11, v3
	s_waitcnt lgkmcnt(6)
	v_cvt_pk_bf16_f32 v38, v42, v28
	s_waitcnt lgkmcnt(4)
	v_cvt_pk_bf16_f32 v39, v44, v46
	s_waitcnt lgkmcnt(2)
	v_cvt_pk_bf16_f32 v40, v48, v50
	s_waitcnt lgkmcnt(0)
	v_cvt_pk_bf16_f32 v41, v52, v54
	v_lshl_add_u64 v[58:59], v[56:57], 0, v[4:5]
	global_store_dwordx4 v[58:59], v[38:41], off
	v_or_b32_e32 v3, s6, v33
	v_lshlrev_b32_e32 v4, 11, v3
	v_cvt_pk_bf16_f32 v38, v43, v29
	v_cvt_pk_bf16_f32 v39, v45, v47
	v_cvt_pk_bf16_f32 v40, v49, v51
	v_cvt_pk_bf16_f32 v41, v53, v55
	ds_read2_b32 v[42:43], v32 offset0:49 offset1:57
	ds_read2_b32 v[44:45], v32 offset0:16 offset1:24
	ds_read2_b32 v[46:47], v32 offset0:82 offset1:90
	ds_read2_b32 v[48:49], v32 offset0:115 offset1:123
	ds_read2_b32 v[50:51], v32 offset0:148 offset1:156
	ds_read2_b32 v[52:53], v32 offset0:181 offset1:189
	ds_read2_b32 v[54:55], v32 offset0:214 offset1:222
	ds_read2_b32 v[58:59], v32 offset0:247 offset1:255
	v_or_b32_e32 v3, s6, v35
	v_lshl_add_u64 v[28:29], v[56:57], 0, v[4:5]
	v_lshlrev_b32_e32 v4, 11, v3
	v_or_b32_e32 v3, s6, v36
	global_store_dwordx4 v[28:29], v[38:41], off
	v_lshl_add_u64 v[28:29], v[56:57], 0, v[4:5]
	v_lshlrev_b32_e32 v4, 11, v3
	s_waitcnt lgkmcnt(6)
	v_cvt_pk_bf16_f32 v38, v44, v42
	s_waitcnt lgkmcnt(4)
	v_cvt_pk_bf16_f32 v39, v46, v48
	s_waitcnt lgkmcnt(2)
	v_cvt_pk_bf16_f32 v40, v50, v52
	s_waitcnt lgkmcnt(0)
	v_cvt_pk_bf16_f32 v41, v54, v58
	global_store_dwordx4 v[28:29], v[38:41], off
	v_lshl_add_u64 v[28:29], v[56:57], 0, v[4:5]
	s_mov_b64 s[4:5], 0
	v_cvt_pk_bf16_f32 v38, v45, v43
	v_cvt_pk_bf16_f32 v39, v47, v49
	v_cvt_pk_bf16_f32 v40, v51, v53
	v_cvt_pk_bf16_f32 v41, v55, v59
	global_store_dwordx4 v[28:29], v[38:41], off
	s_waitcnt lgkmcnt(0)

; #define LDS_WAIT() asm volatile("s_waitcnt lgkmcnt(0)" ::: "memory")
; __device__ __forceinline__ void transpose_item(const float* W, int ldw, int nblk, bf16* WT, int ldt, LAS float* scr, int item, int lane) {
;     const int kb = item / nblk, nb = item % nblk, k0 = 64 * kb, n0 = 32 * nb;
; #pragma unroll 8
;     for (int i = 0; i < 32; ++i) { const int kk = 2 * i + (lane >> 5); scr[kk * 33 + (lane & 31)] = W[(size_t)(k0 + kk) * ldw + n0 + (lane & 31)]; }
;     LDS_WAIT(); asm volatile("" ::: "memory");
.LBB0_25:
	s_lshl_b32 s11, s0, 1
	s_lshl_b32 s12, s5, 1
	v_or_b32_e32 v4, s12, v30
	s_add_i32 s14, s11, 4
	s_add_i32 s15, s12, 4
	v_mov_b32_e32 v41, v5
	s_add_i32 s17, s12, 8
	v_lshlrev_b64 v[54:55], 12, v[4:5]
	v_or_b32_e32 v40, s14, v3
	v_or_b32_e32 v4, s15, v30
	v_mov_b32_e32 v39, v5
	v_or_b32_e32 v38, s11, v3
	s_add_i32 s19, s12, 12
	v_lshlrev_b64 v[40:41], 12, v[40:41]
	v_lshlrev_b64 v[56:57], 12, v[4:5]
	v_or_b32_e32 v4, s17, v30
	s_add_i32 s16, s11, 8
	s_add_i32 s18, s11, 12
	s_add_i32 s35, s12, 16
	v_lshlrev_b64 v[38:39], 12, v[38:39]
	v_lshl_add_u64 v[54:55], v[28:29], 0, v[54:55]
	v_lshl_add_u64 v[40:41], v[28:29], 0, v[40:41]
	v_lshlrev_b64 v[58:59], 12, v[4:5]
	v_or_b32_e32 v4, s19, v30
	v_mov_b32_e32 v43, v5
	v_mov_b32_e32 v45, v5
	s_add_i32 s41, s12, 20
	v_or_b32_e32 v42, s16, v3
	v_or_b32_e32 v44, s18, v3
	v_lshl_add_u64 v[38:39], v[28:29], 0, v[38:39]
	v_lshl_add_u64 v[56:57], v[28:29], 0, v[56:57]
	global_load_dword v37, v[54:55], off nt
	global_load_dword v70, v[38:39], off nt
	global_load_dword v71, v[56:57], off nt
	global_load_dword v72, v[40:41], off nt
	v_lshlrev_b64 v[40:41], 12, v[4:5]
	v_or_b32_e32 v4, s35, v30
	s_add_i32 s33, s11, 16
	s_add_i32 s40, s11, 20
	s_add_i32 s55, s12, 24
	v_lshlrev_b64 v[42:43], 12, v[42:43]
	v_lshlrev_b64 v[44:45], 12, v[44:45]
	v_lshl_add_u64 v[38:39], v[28:29], 0, v[58:59]
	v_lshl_add_u64 v[40:41], v[28:29], 0, v[40:41]
	v_lshlrev_b64 v[54:55], 12, v[4:5]
	v_or_b32_e32 v4, s41, v30
	v_mov_b32_e32 v47, v5
	v_mov_b32_e32 v49, v5
	s_add_i32 s54, s11, 24
	s_add_i32 s56, s11, 28
	s_add_i32 s57, s12, 28
	v_or_b32_e32 v46, s33, v3
	v_or_b32_e32 v48, s40, v3
	v_lshl_add_u64 v[42:43], v[28:29], 0, v[42:43]
	v_lshl_add_u64 v[44:45], v[28:29], 0, v[44:45]
	global_load_dword v73, v[38:39], off nt
	global_load_dword v74, v[42:43], off nt
	global_load_dword v75, v[40:41], off nt
	global_load_dword v76, v[44:45], off nt
	v_lshlrev_b64 v[40:41], 12, v[4:5]
	v_or_b32_e32 v4, s55, v30
	v_mov_b32_e32 v51, v5
	v_mov_b32_e32 v53, v5
	v_or_b32_e32 v50, s54, v3
	v_or_b32_e32 v52, s56, v3
	v_lshlrev_b64 v[46:47], 12, v[46:47]
	v_lshlrev_b64 v[48:49], 12, v[48:49]
	v_lshl_add_u64 v[38:39], v[28:29], 0, v[54:55]
	v_lshl_add_u64 v[40:41], v[28:29], 0, v[40:41]
	v_lshlrev_b64 v[42:43], 12, v[4:5]
	v_or_b32_e32 v4, s57, v30
	v_lshlrev_b64 v[50:51], 12, v[50:51]
	v_lshlrev_b64 v[52:53], 12, v[52:53]
	v_lshl_add_u64 v[46:47], v[28:29], 0, v[46:47]
	v_lshl_add_u64 v[48:49], v[28:29], 0, v[48:49]
	global_load_dword v77, v[38:39], off nt
	global_load_dword v78, v[46:47], off nt
	global_load_dword v79, v[40:41], off nt
	global_load_dword v80, v[48:49], off nt
	v_lshl_add_u64 v[38:39], v[28:29], 0, v[42:43]
	v_lshlrev_b64 v[40:41], 12, v[4:5]
	v_lshl_add_u64 v[50:51], v[28:29], 0, v[50:51]
	v_lshl_add_u64 v[52:53], v[28:29], 0, v[52:53]
	v_lshl_add_u64 v[40:41], v[28:29], 0, v[40:41]
	global_load_dword v4, v[38:39], off nt
	global_load_dword v81, v[50:51], off nt
	global_load_dword v82, v[40:41], off nt
	global_load_dword v83, v[52:53], off nt
	v_or_b32_e32 v40, s11, v1
	v_or_b32_e32 v38, s12, v2
	s_add_i32 s5, s5, 16
	s_add_i32 s0, s0, 16
	s_add_i32 s7, s7, -16
	v_mad_u64_u32 v[38:39], s[12:13], v38, s8, v[8:9]
	v_mad_u64_u32 v[40:41], s[12:13], v40, s8, v[8:9]
	v_or_b32_e32 v39, s14, v1
	v_or_b32_e32 v41, s15, v2
	v_or_b32_e32 v48, s16, v1
	v_or_b32_e32 v46, s17, v2
	v_or_b32_e32 v52, s18, v1
	v_or_b32_e32 v50, s19, v2
	v_or_b32_e32 v56, s33, v1
	v_or_b32_e32 v54, s35, v2
	v_or_b32_e32 v60, s40, v1
	v_or_b32_e32 v58, s41, v2
	v_or_b32_e32 v64, s54, v1
	v_or_b32_e32 v62, s55, v2
	v_or_b32_e32 v68, s56, v1
	v_or_b32_e32 v66, s57, v2
	s_cmp_lg_u32 s7, 0
	v_mad_u64_u32 v[42:43], s[12:13], v41, s8, v[8:9]
	v_mad_u64_u32 v[44:45], s[12:13], v39, s8, v[8:9]
	v_mad_u64_u32 v[46:47], s[12:13], v46, s8, v[8:9]
	v_mad_u64_u32 v[48:49], s[12:13], v48, s8, v[8:9]
	v_mad_u64_u32 v[50:51], s[12:13], v50, s8, v[8:9]
	v_mad_u64_u32 v[52:53], s[12:13], v52, s8, v[8:9]
	v_mad_u64_u32 v[54:55], s[12:13], v54, s8, v[8:9]
	v_mad_u64_u32 v[56:57], s[12:13], v56, s8, v[8:9]
	v_mad_u64_u32 v[58:59], s[12:13], v58, s8, v[8:9]
	v_mad_u64_u32 v[60:61], s[12:13], v60, s8, v[8:9]
	v_mad_u64_u32 v[62:63], s[12:13], v62, s8, v[8:9]
	v_mad_u64_u32 v[64:65], s[12:13], v64, s8, v[8:9]
	v_mad_u64_u32 v[66:67], s[12:13], v66, s8, v[8:9]
	v_mad_u64_u32 v[68:69], s[12:13], v68, s8, v[8:9]
	s_waitcnt vmcnt(15)
	ds_write_b32 v38, v37
	s_waitcnt vmcnt(14)
	ds_write_b32 v40, v70
	s_waitcnt vmcnt(13)
	ds_write_b32 v42, v71
	s_waitcnt vmcnt(12)
	ds_write_b32 v44, v72
	s_waitcnt vmcnt(11)
	ds_write_b32 v46, v73
	s_waitcnt vmcnt(10)
	ds_write_b32 v48, v74
	s_waitcnt vmcnt(9)
	ds_write_b32 v50, v75
	s_waitcnt vmcnt(8)
	ds_write_b32 v52, v76
	s_waitcnt vmcnt(7)
	ds_write_b32 v54, v77
	s_waitcnt vmcnt(6)
	ds_write_b32 v56, v78
	s_waitcnt vmcnt(5)
	ds_write_b32 v58, v79
	s_waitcnt vmcnt(4)
	ds_write_b32 v60, v80
	s_waitcnt vmcnt(3)
	ds_write_b32 v62, v4
	s_waitcnt vmcnt(2)
	ds_write_b32 v64, v81
	s_waitcnt vmcnt(1)
	ds_write_b32 v66, v82
	s_waitcnt vmcnt(0)
	ds_write_b32 v68, v83
	s_cbranch_scc1 .LBB0_25
; #define GAS __attribute__((address_space(1)))
; #define LAS __attribute__((address_space(3)))
; #define LDS_WAIT() asm volatile("s_waitcnt lgkmcnt(0)" ::: "memory")
; __device__ __forceinline__ unsigned pk2(float lo, float hi) { return pg8::cvt_pk_bf16_c(lo, hi); }
; __device__ __forceinline__ void transpose_item(const float* W, int ldw, int nblk, bf16* WT, int ldt, LAS float* scr, int item, int lane) {
;     ...
;     const int c = lane & 7;
; #pragma unroll
;     for (int j = 0; j < 4; ++j) { const int n = (lane >> 3) + 8 * j; const LAS float* s = scr + (8 * c) * 33 + n;
;         v4u o; o.x = pk2(s[0 * 33], s[1 * 33]); o.y = pk2(s[2 * 33], s[3 * 33]); o.z = pk2(s[4 * 33], s[5 * 33]); o.w = pk2(s[6 * 33], s[7 * 33]);
;         *(GAS v4u*)(WT + (size_t)(n0 + n) * ldt + k0 + 8 * c) = o; }
;     LDS_WAIT(); asm volatile("" ::: "memory");
	s_waitcnt lgkmcnt(0)
	ds_read2_b32 v[28:29], v32 offset0:33 offset1:41
	ds_read2_b32 v[42:43], v32 offset1:8
	ds_read2_b32 v[44:45], v32 offset0:66 offset1:74
	ds_read2_b32 v[46:47], v32 offset0:99 offset1:107
	ds_read2_b32 v[48:49], v32 offset0:132 offset1:140
	ds_read2_b32 v[50:51], v32 offset0:165 offset1:173
	ds_read2_b32 v[52:53], v32 offset0:198 offset1:206
	ds_read2_b32 v[54:55], v32 offset0:231 offset1:239
	s_lshl_b32 s0, s4, 1
	v_or_b32_e32 v3, s6, v31
	v_lshl_add_u64 v[56:57], v[14:15], 0, s[0:1]
	v_lshlrev_b32_e32 v4, 12, v3
	s_waitcnt lgkmcnt(6)
	v_cvt_pk_bf16_f32 v38, v42, v28
	s_waitcnt lgkmcnt(4)
	v_cvt_pk_bf16_f32 v39, v44, v46
	s_waitcnt lgkmcnt(2)
	v_cvt_pk_bf16_f32 v40, v48, v50
	s_waitcnt lgkmcnt(0)
	v_cvt_pk_bf16_f32 v41, v52, v54
	v_lshl_add_u64 v[58:59], v[56:57], 0, v[4:5]
	global_store_dwordx4 v[58:59], v[38:41], off
	v_or_b32_e32 v3, s6, v33
	v_lshlrev_b32_e32 v4, 12, v3
	v_cvt_pk_bf16_f32 v38, v43, v29
	v_cvt_pk_bf16_f32 v39, v45, v47
	v_cvt_pk_bf16_f32 v40, v49, v51
	v_cvt_pk_bf16_f32 v41, v53, v55
	ds_read2_b32 v[42:43], v32 offset0:49 offset1:57
	ds_read2_b32 v[44:45], v32 offset0:16 offset1:24
	ds_read2_b32 v[46:47], v32 offset0:82 offset1:90
	ds_read2_b32 v[48:49], v32 offset0:115 offset1:123
	ds_read2_b32 v[50:51], v32 offset0:148 offset1:156
	ds_read2_b32 v[52:53], v32 offset0:181 offset1:189
	ds_read2_b32 v[54:55], v32 offset0:214 offset1:222
	ds_read2_b32 v[58:59], v32 offset0:247 offset1:255
	v_or_b32_e32 v3, s6, v35
	v_lshl_add_u64 v[28:29], v[56:57], 0, v[4:5]
	v_lshlrev_b32_e32 v4, 12, v3
	v_or_b32_e32 v3, s6, v36
	global_store_dwordx4 v[28:29], v[38:41], off
	v_lshl_add_u64 v[28:29], v[56:57], 0, v[4:5]
	v_lshlrev_b32_e32 v4, 12, v3
	s_waitcnt lgkmcnt(6)
	v_cvt_pk_bf16_f32 v38, v44, v42
	s_waitcnt lgkmcnt(4)
	v_cvt_pk_bf16_f32 v39, v46, v48
	s_waitcnt lgkmcnt(2)
	v_cvt_pk_bf16_f32 v40, v50, v52
	s_waitcnt lgkmcnt(0)
	v_cvt_pk_bf16_f32 v41, v54, v58
	global_store_dwordx4 v[28:29], v[38:41], off
	v_lshl_add_u64 v[28:29], v[56:57], 0, v[4:5]
	s_nop 0
	v_cvt_pk_bf16_f32 v38, v45, v43
	v_cvt_pk_bf16_f32 v39, v47, v49
	v_cvt_pk_bf16_f32 v40, v51, v53
	v_cvt_pk_bf16_f32 v41, v55, v59
	global_store_dwordx4 v[28:29], v[38:41], off
	s_waitcnt lgkmcnt(0)

; #define LDS_WAIT() asm volatile("s_waitcnt lgkmcnt(0)" ::: "memory")
; __device__ __forceinline__ void transpose_item(const float* W, int ldw, int nblk, bf16* WT, int ldt, LAS float* scr, int item, int lane) {
;     const int kb = item / nblk, nb = item % nblk, k0 = 64 * kb, n0 = 32 * nb;
; #pragma unroll 8
;     for (int i = 0; i < 32; ++i) { const int kk = 2 * i + (lane >> 5); scr[kk * 33 + (lane & 31)] = W[(size_t)(k0 + kk) * ldw + n0 + (lane & 31)]; }
;     LDS_WAIT(); asm volatile("" ::: "memory");
.LBB0_30:
	s_lshl_b32 s11, s6, 1
	s_lshl_b32 s12, s0, 1
	v_or_b32_e32 v4, s12, v30
	s_add_i32 s14, s11, 4
	s_add_i32 s15, s12, 4
	v_mov_b32_e32 v41, v5
	s_add_i32 s17, s12, 8
	v_lshlrev_b64 v[54:55], 12, v[4:5]
	v_or_b32_e32 v40, s14, v3
	v_or_b32_e32 v4, s15, v30
	v_mov_b32_e32 v39, v5
	v_or_b32_e32 v38, s11, v3
	s_add_i32 s19, s12, 12
	v_lshlrev_b64 v[40:41], 12, v[40:41]
	v_lshlrev_b64 v[56:57], 12, v[4:5]
	v_or_b32_e32 v4, s17, v30
	s_add_i32 s16, s11, 8
	s_add_i32 s18, s11, 12
	s_add_i32 s35, s12, 16
	v_lshlrev_b64 v[38:39], 12, v[38:39]
	v_lshl_add_u64 v[54:55], v[28:29], 0, v[54:55]
	v_lshl_add_u64 v[40:41], v[28:29], 0, v[40:41]
	v_lshlrev_b64 v[58:59], 12, v[4:5]
	v_or_b32_e32 v4, s19, v30
	v_mov_b32_e32 v43, v5
	v_mov_b32_e32 v45, v5
	s_add_i32 s41, s12, 20
	v_or_b32_e32 v42, s16, v3
	v_or_b32_e32 v44, s18, v3
	v_lshl_add_u64 v[38:39], v[28:29], 0, v[38:39]
	v_lshl_add_u64 v[56:57], v[28:29], 0, v[56:57]
	global_load_dword v37, v[54:55], off nt
	global_load_dword v70, v[38:39], off nt
	global_load_dword v71, v[56:57], off nt
	global_load_dword v72, v[40:41], off nt
	v_lshlrev_b64 v[40:41], 12, v[4:5]
	v_or_b32_e32 v4, s35, v30
	s_add_i32 s33, s11, 16
	s_add_i32 s40, s11, 20
	s_add_i32 s55, s12, 24
	v_lshlrev_b64 v[42:43], 12, v[42:43]
	v_lshlrev_b64 v[44:45], 12, v[44:45]
	v_lshl_add_u64 v[38:39], v[28:29], 0, v[58:59]
	v_lshl_add_u64 v[40:41], v[28:29], 0, v[40:41]
	v_lshlrev_b64 v[54:55], 12, v[4:5]
	v_or_b32_e32 v4, s41, v30
	v_mov_b32_e32 v47, v5
	v_mov_b32_e32 v49, v5
	s_add_i32 s54, s11, 24
	s_add_i32 s56, s11, 28
	s_add_i32 s57, s12, 28
	v_or_b32_e32 v46, s33, v3
	v_or_b32_e32 v48, s40, v3
	v_lshl_add_u64 v[42:43], v[28:29], 0, v[42:43]
	v_lshl_add_u64 v[44:45], v[28:29], 0, v[44:45]
	global_load_dword v73, v[38:39], off nt
	global_load_dword v74, v[42:43], off nt
	global_load_dword v75, v[40:41], off nt
	global_load_dword v76, v[44:45], off nt
	v_lshlrev_b64 v[40:41], 12, v[4:5]
	v_or_b32_e32 v4, s55, v30
	v_mov_b32_e32 v51, v5
	v_mov_b32_e32 v53, v5
	v_or_b32_e32 v50, s54, v3
	v_or_b32_e32 v52, s56, v3
	v_lshlrev_b64 v[46:47], 12, v[46:47]
	v_lshlrev_b64 v[48:49], 12, v[48:49]
	v_lshl_add_u64 v[38:39], v[28:29], 0, v[54:55]
	v_lshl_add_u64 v[40:41], v[28:29], 0, v[40:41]
	v_lshlrev_b64 v[42:43], 12, v[4:5]
	v_or_b32_e32 v4, s57, v30
	v_lshlrev_b64 v[50:51], 12, v[50:51]
	v_lshlrev_b64 v[52:53], 12, v[52:53]
	v_lshl_add_u64 v[46:47], v[28:29], 0, v[46:47]
	v_lshl_add_u64 v[48:49], v[28:29], 0, v[48:49]
	global_load_dword v77, v[38:39], off nt
	global_load_dword v78, v[46:47], off nt
	global_load_dword v79, v[40:41], off nt
	global_load_dword v80, v[48:49], off nt
	v_lshl_add_u64 v[38:39], v[28:29], 0, v[42:43]
	v_lshlrev_b64 v[40:41], 12, v[4:5]
	v_lshl_add_u64 v[50:51], v[28:29], 0, v[50:51]
	v_lshl_add_u64 v[52:53], v[28:29], 0, v[52:53]
	v_lshl_add_u64 v[40:41], v[28:29], 0, v[40:41]
	global_load_dword v4, v[38:39], off nt
	global_load_dword v81, v[50:51], off nt
	global_load_dword v82, v[40:41], off nt
	global_load_dword v83, v[52:53], off nt
	v_or_b32_e32 v40, s11, v1
	v_or_b32_e32 v38, s12, v2
	s_add_i32 s0, s0, 16
	s_add_i32 s6, s6, 16
	s_add_i32 s7, s7, -16
	v_mad_u64_u32 v[38:39], s[12:13], v38, s8, v[8:9]
	v_mad_u64_u32 v[40:41], s[12:13], v40, s8, v[8:9]
	v_or_b32_e32 v39, s14, v1
	v_or_b32_e32 v41, s15, v2
	v_or_b32_e32 v48, s16, v1
	v_or_b32_e32 v46, s17, v2
	v_or_b32_e32 v52, s18, v1
	v_or_b32_e32 v50, s19, v2
	v_or_b32_e32 v56, s33, v1
	v_or_b32_e32 v54, s35, v2
	v_or_b32_e32 v60, s40, v1
	v_or_b32_e32 v58, s41, v2
	v_or_b32_e32 v64, s54, v1
	v_or_b32_e32 v62, s55, v2
	v_or_b32_e32 v68, s56, v1
	v_or_b32_e32 v66, s57, v2
	s_cmp_lg_u32 s7, 0
	v_mad_u64_u32 v[42:43], s[12:13], v41, s8, v[8:9]
	v_mad_u64_u32 v[44:45], s[12:13], v39, s8, v[8:9]
	v_mad_u64_u32 v[46:47], s[12:13], v46, s8, v[8:9]
	v_mad_u64_u32 v[48:49], s[12:13], v48, s8, v[8:9]
	v_mad_u64_u32 v[50:51], s[12:13], v50, s8, v[8:9]
	v_mad_u64_u32 v[52:53], s[12:13], v52, s8, v[8:9]
	v_mad_u64_u32 v[54:55], s[12:13], v54, s8, v[8:9]
	v_mad_u64_u32 v[56:57], s[12:13], v56, s8, v[8:9]
	v_mad_u64_u32 v[58:59], s[12:13], v58, s8, v[8:9]
	v_mad_u64_u32 v[60:61], s[12:13], v60, s8, v[8:9]
	v_mad_u64_u32 v[62:63], s[12:13], v62, s8, v[8:9]
	v_mad_u64_u32 v[64:65], s[12:13], v64, s8, v[8:9]
	v_mad_u64_u32 v[66:67], s[12:13], v66, s8, v[8:9]
	v_mad_u64_u32 v[68:69], s[12:13], v68, s8, v[8:9]
	s_waitcnt vmcnt(15)
	ds_write_b32 v38, v37
	s_waitcnt vmcnt(14)
	ds_write_b32 v40, v70
	s_waitcnt vmcnt(13)
	ds_write_b32 v42, v71
	s_waitcnt vmcnt(12)
	ds_write_b32 v44, v72
	s_waitcnt vmcnt(11)
	ds_write_b32 v46, v73
	s_waitcnt vmcnt(10)
	ds_write_b32 v48, v74
	s_waitcnt vmcnt(9)
	ds_write_b32 v50, v75
	s_waitcnt vmcnt(8)
	ds_write_b32 v52, v76
	s_waitcnt vmcnt(7)
	ds_write_b32 v54, v77
	s_waitcnt vmcnt(6)
	ds_write_b32 v56, v78
	s_waitcnt vmcnt(5)
	ds_write_b32 v58, v79
	s_waitcnt vmcnt(4)
	ds_write_b32 v60, v80
	s_waitcnt vmcnt(3)
	ds_write_b32 v62, v4
	s_waitcnt vmcnt(2)
	ds_write_b32 v64, v81
	s_waitcnt vmcnt(1)
	ds_write_b32 v66, v82
	s_waitcnt vmcnt(0)
	ds_write_b32 v68, v83
	s_cbranch_scc1 .LBB0_30
; #define GAS __attribute__((address_space(1)))
; #define LAS __attribute__((address_space(3)))
; #define LDS_WAIT() asm volatile("s_waitcnt lgkmcnt(0)" ::: "memory")
; __device__ __forceinline__ unsigned pk2(float lo, float hi) { return pg8::cvt_pk_bf16_c(lo, hi); }
; __device__ __forceinline__ void transpose_item(const float* W, int ldw, int nblk, bf16* WT, int ldt, LAS float* scr, int item, int lane) {
;     ...
;     const int c = lane & 7;
; #pragma unroll
;     for (int j = 0; j < 4; ++j) { const int n = (lane >> 3) + 8 * j; const LAS float* s = scr + (8 * c) * 33 + n;
;         v4u o; o.x = pk2(s[0 * 33], s[1 * 33]); o.y = pk2(s[2 * 33], s[3 * 33]); o.z = pk2(s[4 * 33], s[5 * 33]); o.w = pk2(s[6 * 33], s[7 * 33]);
;         *(GAS v4u*)(WT + (size_t)(n0 + n) * ldt + k0 + 8 * c) = o; }
;     LDS_WAIT(); asm volatile("" ::: "memory");
	s_waitcnt lgkmcnt(0)
	ds_read2_b32 v[28:29], v32 offset0:33 offset1:41
	ds_read2_b32 v[42:43], v32 offset1:8
	ds_read2_b32 v[44:45], v32 offset0:66 offset1:74
	ds_read2_b32 v[46:47], v32 offset0:99 offset1:107
	ds_read2_b32 v[48:49], v32 offset0:132 offset1:140
	ds_read2_b32 v[50:51], v32 offset0:165 offset1:173
	ds_read2_b32 v[52:53], v32 offset0:198 offset1:206
	ds_read2_b32 v[54:55], v32 offset0:231 offset1:239
	s_lshl_b32 s0, s5, 1
	v_or_b32_e32 v3, s4, v31
	v_lshl_add_u64 v[56:57], v[18:19], 0, s[0:1]
	v_lshlrev_b32_e32 v4, 12, v3
	s_waitcnt lgkmcnt(6)
	v_cvt_pk_bf16_f32 v38, v42, v28
	s_waitcnt lgkmcnt(4)
	v_cvt_pk_bf16_f32 v39, v44, v46
	s_waitcnt lgkmcnt(2)
	v_cvt_pk_bf16_f32 v40, v48, v50
	s_waitcnt lgkmcnt(0)
	v_cvt_pk_bf16_f32 v41, v52, v54
	v_lshl_add_u64 v[58:59], v[56:57], 0, v[4:5]
	global_store_dwordx4 v[58:59], v[38:41], off
	v_or_b32_e32 v3, s4, v33
	v_lshlrev_b32_e32 v4, 12, v3
	v_cvt_pk_bf16_f32 v38, v43, v29
	v_cvt_pk_bf16_f32 v39, v45, v47
	v_cvt_pk_bf16_f32 v40, v49, v51
	v_cvt_pk_bf16_f32 v41, v53, v55
	ds_read2_b32 v[42:43], v32 offset0:49 offset1:57
	ds_read2_b32 v[44:45], v32 offset0:16 offset1:24
	ds_read2_b32 v[46:47], v32 offset0:82 offset1:90
	ds_read2_b32 v[48:49], v32 offset0:115 offset1:123
	ds_read2_b32 v[50:51], v32 offset0:148 offset1:156
	ds_read2_b32 v[52:53], v32 offset0:181 offset1:189
	ds_read2_b32 v[54:55], v32 offset0:214 offset1:222
	ds_read2_b32 v[58:59], v32 offset0:247 offset1:255
	v_or_b32_e32 v3, s4, v35
	v_lshl_add_u64 v[28:29], v[56:57], 0, v[4:5]
	v_lshlrev_b32_e32 v4, 12, v3
	v_or_b32_e32 v3, s4, v36
	global_store_dwordx4 v[28:29], v[38:41], off
	v_lshl_add_u64 v[28:29], v[56:57], 0, v[4:5]
	v_lshlrev_b32_e32 v4, 12, v3
	s_waitcnt lgkmcnt(6)
	v_cvt_pk_bf16_f32 v38, v44, v42
	s_waitcnt lgkmcnt(4)
	v_cvt_pk_bf16_f32 v39, v46, v48
	s_waitcnt lgkmcnt(2)
	v_cvt_pk_bf16_f32 v40, v50, v52
	s_waitcnt lgkmcnt(0)
	v_cvt_pk_bf16_f32 v41, v54, v58
	global_store_dwordx4 v[28:29], v[38:41], off
	v_lshl_add_u64 v[28:29], v[56:57], 0, v[4:5]
	s_nop 0
	v_cvt_pk_bf16_f32 v38, v45, v43
	v_cvt_pk_bf16_f32 v39, v47, v49
	v_cvt_pk_bf16_f32 v40, v51, v53
	v_cvt_pk_bf16_f32 v41, v55, v59
	global_store_dwordx4 v[28:29], v[38:41], off
	s_waitcnt lgkmcnt(0)

; #define GAS __attribute__((address_space(1)))
; #define LAS __attribute__((address_space(3)))
; #define LDS_WAIT() asm volatile("s_waitcnt lgkmcnt(0)" ::: "memory")
; __device__ __forceinline__ unsigned pk2(float lo, float hi) { return pg8::cvt_pk_bf16_c(lo, hi); }
; __device__ __forceinline__ void transpose_item(const float* W, int ldw, int nblk, bf16* WT, int ldt, LAS float* scr, int item, int lane) {
;     ...
; #pragma unroll 8
;     for (int i = 0; i < 32; ++i) { const int kk = 2 * i + (lane >> 5); scr[kk * 33 + (lane & 31)] = W[(size_t)(k0 + kk) * ldw + n0 + (lane & 31)]; }
;     LDS_WAIT(); asm volatile("" ::: "memory");
;     const int c = lane & 7;
; #pragma unroll
;     for (int j = 0; j < 4; ++j) { const int n = (lane >> 3) + 8 * j; const LAS float* s = scr + (8 * c) * 33 + n;
;         v4u o; o.x = pk2(s[0 * 33], s[1 * 33]); o.y = pk2(s[2 * 33], s[3 * 33]); o.z = pk2(s[4 * 33], s[5 * 33]); o.w = pk2(s[6 * 33], s[7 * 33]);
;         *(GAS v4u*)(WT + (size_t)(n0 + n) * ldt + k0 + 8 * c) = o; }
;     LDS_WAIT(); asm volatile("" ::: "memory");
.LBB0_35:
	s_lshl_b32 s11, s0, 1
	s_lshl_b32 s14, s6, 1
	v_or_b32_e32 v30, s11, v3
	v_or_b32_e32 v37, s14, v4
	s_add_i32 s15, s11, 4
	s_add_i32 s16, s14, 4
	s_add_i32 s17, s11, 8
	s_add_i32 s18, s14, 8
	s_add_i32 s19, s11, 12
	s_add_i32 s33, s14, 12
	s_add_i32 s35, s11, 16
	s_add_i32 s40, s14, 16
	s_add_i32 s41, s11, 20
	s_add_i32 s54, s14, 20
	s_add_i32 s55, s11, 24
	s_add_i32 s56, s14, 24
	s_add_i32 s57, s11, 28
	s_add_i32 s58, s14, 28
	v_mad_u64_u32 v[38:39], s[12:13], v37, s9, v[28:29]
	v_mad_u64_u32 v[40:41], s[12:13], v30, s9, v[28:29]
	v_or_b32_e32 v30, s15, v3
	v_or_b32_e32 v37, s16, v4
	v_or_b32_e32 v48, s17, v3
	v_or_b32_e32 v46, s18, v4
	v_or_b32_e32 v52, s19, v3
	v_or_b32_e32 v50, s33, v4
	v_or_b32_e32 v56, s35, v3
	v_or_b32_e32 v54, s40, v4
	v_or_b32_e32 v60, s41, v3
	v_or_b32_e32 v58, s54, v4
	v_or_b32_e32 v64, s55, v3
	v_or_b32_e32 v62, s56, v4
	v_or_b32_e32 v68, s57, v3
	v_or_b32_e32 v66, s58, v4
	v_mad_u64_u32 v[42:43], s[12:13], v37, s9, v[28:29]
	v_mad_u64_u32 v[44:45], s[12:13], v30, s9, v[28:29]
	v_mad_u64_u32 v[46:47], s[12:13], v46, s9, v[28:29]
	v_mad_u64_u32 v[48:49], s[12:13], v48, s9, v[28:29]
	v_mad_u64_u32 v[50:51], s[12:13], v50, s9, v[28:29]
	v_mad_u64_u32 v[52:53], s[12:13], v52, s9, v[28:29]
	v_mad_u64_u32 v[54:55], s[12:13], v54, s9, v[28:29]
	v_mad_u64_u32 v[56:57], s[12:13], v56, s9, v[28:29]
	v_mad_u64_u32 v[58:59], s[12:13], v58, s9, v[28:29]
	v_mad_u64_u32 v[60:61], s[12:13], v60, s9, v[28:29]
	v_mad_u64_u32 v[62:63], s[12:13], v62, s9, v[28:29]
	v_mad_u64_u32 v[64:65], s[12:13], v64, s9, v[28:29]
	v_mad_u64_u32 v[66:67], s[12:13], v66, s9, v[28:29]
	v_mad_u64_u32 v[68:69], s[12:13], v68, s9, v[28:29]
	global_load_dword v30, v[38:39], off nt
	global_load_dword v37, v[40:41], off nt
	global_load_dword v70, v[42:43], off nt
	global_load_dword v71, v[44:45], off nt
	global_load_dword v72, v[46:47], off nt
	global_load_dword v73, v[48:49], off nt
	global_load_dword v74, v[50:51], off nt
	global_load_dword v75, v[52:53], off nt
	global_load_dword v76, v[54:55], off nt
	global_load_dword v77, v[56:57], off nt
	global_load_dword v78, v[58:59], off nt
	global_load_dword v79, v[60:61], off nt
	global_load_dword v80, v[62:63], off nt
	global_load_dword v81, v[64:65], off nt
	global_load_dword v82, v[66:67], off nt
	global_load_dword v83, v[68:69], off nt
	v_or_b32_e32 v40, s11, v1
	v_or_b32_e32 v38, s14, v2
	s_add_i32 s6, s6, 16
	s_add_i32 s0, s0, 16
	s_add_i32 s7, s7, -16
	v_mad_u64_u32 v[38:39], s[12:13], v38, s8, v[8:9]
	v_mad_u64_u32 v[40:41], s[12:13], v40, s8, v[8:9]
	v_or_b32_e32 v39, s15, v1
	v_or_b32_e32 v41, s16, v2
	v_or_b32_e32 v48, s17, v1
	v_or_b32_e32 v46, s18, v2
	v_or_b32_e32 v52, s19, v1
	v_or_b32_e32 v50, s33, v2
	v_or_b32_e32 v56, s35, v1
	v_or_b32_e32 v54, s40, v2
	v_or_b32_e32 v60, s41, v1
	v_or_b32_e32 v58, s54, v2
	v_or_b32_e32 v64, s55, v1
	v_or_b32_e32 v62, s56, v2
	v_or_b32_e32 v68, s57, v1
	v_or_b32_e32 v66, s58, v2
	s_cmp_lg_u32 s7, 0
	v_mad_u64_u32 v[42:43], s[12:13], v41, s8, v[8:9]
	v_mad_u64_u32 v[44:45], s[12:13], v39, s8, v[8:9]
	v_mad_u64_u32 v[46:47], s[12:13], v46, s8, v[8:9]
	v_mad_u64_u32 v[48:49], s[12:13], v48, s8, v[8:9]
	v_mad_u64_u32 v[50:51], s[12:13], v50, s8, v[8:9]
	v_mad_u64_u32 v[52:53], s[12:13], v52, s8, v[8:9]
	v_mad_u64_u32 v[54:55], s[12:13], v54, s8, v[8:9]
	v_mad_u64_u32 v[56:57], s[12:13], v56, s8, v[8:9]
	v_mad_u64_u32 v[58:59], s[12:13], v58, s8, v[8:9]
	v_mad_u64_u32 v[60:61], s[12:13], v60, s8, v[8:9]
	v_mad_u64_u32 v[62:63], s[12:13], v62, s8, v[8:9]
	v_mad_u64_u32 v[64:65], s[12:13], v64, s8, v[8:9]
	v_mad_u64_u32 v[66:67], s[12:13], v66, s8, v[8:9]
	v_mad_u64_u32 v[68:69], s[12:13], v68, s8, v[8:9]
	s_waitcnt vmcnt(15)
	ds_write_b32 v38, v30
	s_waitcnt vmcnt(14)
	ds_write_b32 v40, v37
	s_waitcnt vmcnt(13)
	ds_write_b32 v42, v70
	s_waitcnt vmcnt(12)
	ds_write_b32 v44, v71
	s_waitcnt vmcnt(11)
	ds_write_b32 v46, v72
	s_waitcnt vmcnt(10)
	ds_write_b32 v48, v73
	s_waitcnt vmcnt(9)
	ds_write_b32 v50, v74
	s_waitcnt vmcnt(8)
	ds_write_b32 v52, v75
	s_waitcnt vmcnt(7)
	ds_write_b32 v54, v76
	s_waitcnt vmcnt(6)
	ds_write_b32 v56, v77
	s_waitcnt vmcnt(5)
	ds_write_b32 v58, v78
	s_waitcnt vmcnt(4)
	ds_write_b32 v60, v79
	s_waitcnt vmcnt(3)
	ds_write_b32 v62, v80
	s_waitcnt vmcnt(2)
	ds_write_b32 v64, v81
	s_waitcnt vmcnt(1)
	ds_write_b32 v66, v82
	s_waitcnt vmcnt(0)
	ds_write_b32 v68, v83
	s_cbranch_scc1 .LBB0_35
	s_waitcnt lgkmcnt(0)
	ds_read2_b32 v[28:29], v32 offset0:33 offset1:41
	ds_read2_b32 v[42:43], v32 offset1:8
	ds_read2_b32 v[44:45], v32 offset0:66 offset1:74
	ds_read2_b32 v[46:47], v32 offset0:99 offset1:107
	ds_read2_b32 v[48:49], v32 offset0:132 offset1:140
	ds_read2_b32 v[50:51], v32 offset0:165 offset1:173
	ds_read2_b32 v[52:53], v32 offset0:198 offset1:206
	ds_read2_b32 v[54:55], v32 offset0:231 offset1:239
	s_lshl_b32 s0, s5, 1
	v_or_b32_e32 v3, s4, v31
	v_lshl_add_u64 v[56:57], v[24:25], 0, s[0:1]
	v_lshlrev_b32_e32 v4, 11, v3
	s_waitcnt lgkmcnt(6)
	v_cvt_pk_bf16_f32 v38, v42, v28
	s_waitcnt lgkmcnt(4)
	v_cvt_pk_bf16_f32 v39, v44, v46
	s_waitcnt lgkmcnt(2)
	v_cvt_pk_bf16_f32 v40, v48, v50
	s_waitcnt lgkmcnt(0)
	v_cvt_pk_bf16_f32 v41, v52, v54
	v_lshl_add_u64 v[58:59], v[56:57], 0, v[4:5]
	global_store_dwordx4 v[58:59], v[38:41], off
	v_or_b32_e32 v3, s4, v33
	v_lshlrev_b32_e32 v4, 11, v3
	v_cvt_pk_bf16_f32 v38, v43, v29
	v_cvt_pk_bf16_f32 v39, v45, v47
	v_cvt_pk_bf16_f32 v40, v49, v51
	v_cvt_pk_bf16_f32 v41, v53, v55
	ds_read2_b32 v[42:43], v32 offset0:49 offset1:57
	ds_read2_b32 v[44:45], v32 offset0:16 offset1:24
	ds_read2_b32 v[46:47], v32 offset0:82 offset1:90
	ds_read2_b32 v[48:49], v32 offset0:115 offset1:123
	ds_read2_b32 v[50:51], v32 offset0:148 offset1:156
	ds_read2_b32 v[52:53], v32 offset0:181 offset1:189
	ds_read2_b32 v[54:55], v32 offset0:214 offset1:222
	ds_read2_b32 v[58:59], v32 offset0:247 offset1:255
	v_or_b32_e32 v3, s4, v35
	v_lshl_add_u64 v[28:29], v[56:57], 0, v[4:5]
	v_lshlrev_b32_e32 v4, 11, v3
	v_or_b32_e32 v3, s4, v36
	global_store_dwordx4 v[28:29], v[38:41], off
	v_lshl_add_u64 v[28:29], v[56:57], 0, v[4:5]
	v_lshlrev_b32_e32 v4, 11, v3
	s_waitcnt lgkmcnt(6)
	v_cvt_pk_bf16_f32 v38, v44, v42
	s_waitcnt lgkmcnt(4)
	v_cvt_pk_bf16_f32 v39, v46, v48
	s_waitcnt lgkmcnt(2)
	v_cvt_pk_bf16_f32 v40, v50, v52
	s_waitcnt lgkmcnt(0)
	v_cvt_pk_bf16_f32 v41, v54, v58
	global_store_dwordx4 v[28:29], v[38:41], off
	v_lshl_add_u64 v[28:29], v[56:57], 0, v[4:5]
	s_nop 0
	v_cvt_pk_bf16_f32 v38, v45, v43
	v_cvt_pk_bf16_f32 v39, v47, v49
	v_cvt_pk_bf16_f32 v40, v51, v53
	v_cvt_pk_bf16_f32 v41, v55, v59
	global_store_dwordx4 v[28:29], v[38:41], off
	s_waitcnt lgkmcnt(0)

; #define GAS __attribute__((address_space(1)))
; #define LAS __attribute__((address_space(3)))
; #define LDS_WAIT() asm volatile("s_waitcnt lgkmcnt(0)" ::: "memory")
; __device__ __forceinline__ unsigned pk2(float lo, float hi) { return pg8::cvt_pk_bf16_c(lo, hi); }
; __device__ __forceinline__ void transpose_item(const float* W, int ldw, int nblk, bf16* WT, int ldt, LAS float* scr, int item, int lane) {
;     ...
; #pragma unroll 8
;     for (int i = 0; i < 32; ++i) { const int kk = 2 * i + (lane >> 5); scr[kk * 33 + (lane & 31)] = W[(size_t)(k0 + kk) * ldw + n0 + (lane & 31)]; }
;     LDS_WAIT(); asm volatile("" ::: "memory");
;     const int c = lane & 7;
; #pragma unroll
;     for (int j = 0; j < 4; ++j) { const int n = (lane >> 3) + 8 * j; const LAS float* s = scr + (8 * c) * 33 + n;
;         v4u o; o.x = pk2(s[0 * 33], s[1 * 33]); o.y = pk2(s[2 * 33], s[3 * 33]); o.z = pk2(s[4 * 33], s[5 * 33]); o.w = pk2(s[6 * 33], s[7 * 33]);
;         *(GAS v4u*)(WT + (size_t)(n0 + n) * ldt + k0 + 8 * c) = o; }
;     LDS_WAIT(); asm volatile("" ::: "memory");
.LBB0_39:
	s_lshl_b32 s11, s0, 1
	s_lshl_b32 s14, s5, 1
	v_or_b32_e32 v30, s11, v3
	v_or_b32_e32 v37, s14, v4
	s_add_i32 s15, s11, 4
	s_add_i32 s16, s14, 4
	s_add_i32 s17, s11, 8
	s_add_i32 s18, s14, 8
	s_add_i32 s19, s11, 12
	s_add_i32 s33, s14, 12
	s_add_i32 s35, s11, 16
	s_add_i32 s40, s14, 16
	s_add_i32 s41, s11, 20
	s_add_i32 s54, s14, 20
	s_add_i32 s55, s11, 24
	s_add_i32 s56, s14, 24
	s_add_i32 s57, s11, 28
	s_add_i32 s58, s14, 28
	v_mad_i64_i32 v[38:39], s[12:13], v37, s9, v[28:29]
	v_mad_i64_i32 v[40:41], s[12:13], v30, s9, v[28:29]
	v_or_b32_e32 v30, s15, v3
	v_or_b32_e32 v37, s16, v4
	v_or_b32_e32 v48, s17, v3
	v_or_b32_e32 v46, s18, v4
	v_or_b32_e32 v52, s19, v3
	v_or_b32_e32 v50, s33, v4
	v_or_b32_e32 v56, s35, v3
	v_or_b32_e32 v54, s40, v4
	v_or_b32_e32 v60, s41, v3
	v_or_b32_e32 v58, s54, v4
	v_or_b32_e32 v64, s55, v3
	v_or_b32_e32 v62, s56, v4
	v_or_b32_e32 v68, s57, v3
	v_or_b32_e32 v66, s58, v4
	v_mad_i64_i32 v[42:43], s[12:13], v37, s9, v[28:29]
	v_mad_i64_i32 v[44:45], s[12:13], v30, s9, v[28:29]
	v_mad_i64_i32 v[46:47], s[12:13], v46, s9, v[28:29]
	v_mad_i64_i32 v[48:49], s[12:13], v48, s9, v[28:29]
	v_mad_i64_i32 v[50:51], s[12:13], v50, s9, v[28:29]
	v_mad_i64_i32 v[52:53], s[12:13], v52, s9, v[28:29]
	v_mad_i64_i32 v[54:55], s[12:13], v54, s9, v[28:29]
	v_mad_i64_i32 v[56:57], s[12:13], v56, s9, v[28:29]
	v_mad_i64_i32 v[58:59], s[12:13], v58, s9, v[28:29]
	v_mad_i64_i32 v[60:61], s[12:13], v60, s9, v[28:29]
	v_mad_i64_i32 v[62:63], s[12:13], v62, s9, v[28:29]
	v_mad_i64_i32 v[64:65], s[12:13], v64, s9, v[28:29]
	v_mad_i64_i32 v[66:67], s[12:13], v66, s9, v[28:29]
	v_mad_i64_i32 v[68:69], s[12:13], v68, s9, v[28:29]
	global_load_dword v30, v[38:39], off nt
	global_load_dword v37, v[40:41], off nt
	global_load_dword v70, v[42:43], off nt
	global_load_dword v71, v[44:45], off nt
	global_load_dword v72, v[46:47], off nt
	global_load_dword v73, v[48:49], off nt
	global_load_dword v74, v[50:51], off nt
	global_load_dword v75, v[52:53], off nt
	global_load_dword v76, v[54:55], off nt
	global_load_dword v77, v[56:57], off nt
	global_load_dword v78, v[58:59], off nt
	global_load_dword v79, v[60:61], off nt
	global_load_dword v80, v[62:63], off nt
	global_load_dword v81, v[64:65], off nt
	global_load_dword v82, v[66:67], off nt
	global_load_dword v83, v[68:69], off nt
	v_or_b32_e32 v40, s11, v1
	v_or_b32_e32 v38, s14, v2
	s_add_i32 s5, s5, 16
	s_add_i32 s0, s0, 16
	s_add_i32 s7, s7, -16
	v_mad_u64_u32 v[38:39], s[12:13], v38, s8, v[8:9]
	v_mad_u64_u32 v[40:41], s[12:13], v40, s8, v[8:9]
	v_or_b32_e32 v39, s15, v1
	v_or_b32_e32 v41, s16, v2
	v_or_b32_e32 v48, s17, v1
	v_or_b32_e32 v46, s18, v2
	v_or_b32_e32 v52, s19, v1
	v_or_b32_e32 v50, s33, v2
	v_or_b32_e32 v56, s35, v1
	v_or_b32_e32 v54, s40, v2
	v_or_b32_e32 v60, s41, v1
	v_or_b32_e32 v58, s54, v2
	v_or_b32_e32 v64, s55, v1
	v_or_b32_e32 v62, s56, v2
	v_or_b32_e32 v68, s57, v1
	v_or_b32_e32 v66, s58, v2
	s_cmp_lg_u32 s7, 0
	v_mad_u64_u32 v[42:43], s[12:13], v41, s8, v[8:9]
	v_mad_u64_u32 v[44:45], s[12:13], v39, s8, v[8:9]
	v_mad_u64_u32 v[46:47], s[12:13], v46, s8, v[8:9]
	v_mad_u64_u32 v[48:49], s[12:13], v48, s8, v[8:9]
	v_mad_u64_u32 v[50:51], s[12:13], v50, s8, v[8:9]
	v_mad_u64_u32 v[52:53], s[12:13], v52, s8, v[8:9]
	v_mad_u64_u32 v[54:55], s[12:13], v54, s8, v[8:9]
	v_mad_u64_u32 v[56:57], s[12:13], v56, s8, v[8:9]
	v_mad_u64_u32 v[58:59], s[12:13], v58, s8, v[8:9]
	v_mad_u64_u32 v[60:61], s[12:13], v60, s8, v[8:9]
	v_mad_u64_u32 v[62:63], s[12:13], v62, s8, v[8:9]
	v_mad_u64_u32 v[64:65], s[12:13], v64, s8, v[8:9]
	v_mad_u64_u32 v[66:67], s[12:13], v66, s8, v[8:9]
	v_mad_u64_u32 v[68:69], s[12:13], v68, s8, v[8:9]
	s_waitcnt vmcnt(15)
	ds_write_b32 v38, v30
	s_waitcnt vmcnt(14)
	ds_write_b32 v40, v37
	s_waitcnt vmcnt(13)
	ds_write_b32 v42, v70
	s_waitcnt vmcnt(12)
	ds_write_b32 v44, v71
	s_waitcnt vmcnt(11)
	ds_write_b32 v46, v72
	s_waitcnt vmcnt(10)
	ds_write_b32 v48, v73
	s_waitcnt vmcnt(9)
	ds_write_b32 v50, v74
	s_waitcnt vmcnt(8)
	ds_write_b32 v52, v75
	s_waitcnt vmcnt(7)
	ds_write_b32 v54, v76
	s_waitcnt vmcnt(6)
	ds_write_b32 v56, v77
	s_waitcnt vmcnt(5)
	ds_write_b32 v58, v78
	s_waitcnt vmcnt(4)
	ds_write_b32 v60, v79
	s_waitcnt vmcnt(3)
	ds_write_b32 v62, v80
	s_waitcnt vmcnt(2)
	ds_write_b32 v64, v81
	s_waitcnt vmcnt(1)
	ds_write_b32 v66, v82
	s_waitcnt vmcnt(0)
	ds_write_b32 v68, v83
	s_cbranch_scc1 .LBB0_39
	s_waitcnt lgkmcnt(0)
	ds_read2_b32 v[28:29], v32 offset0:33 offset1:41
	ds_read2_b32 v[42:43], v32 offset1:8
	ds_read2_b32 v[44:45], v32 offset0:66 offset1:74
	ds_read2_b32 v[46:47], v32 offset0:99 offset1:107
	ds_read2_b32 v[48:49], v32 offset0:132 offset1:140
	ds_read2_b32 v[50:51], v32 offset0:165 offset1:173
	ds_read2_b32 v[52:53], v32 offset0:198 offset1:206
	ds_read2_b32 v[54:55], v32 offset0:231 offset1:239
	v_or_b32_e32 v58, s4, v31
	s_ashr_i32 s7, s6, 31
	v_ashrrev_i32_e32 v59, 31, v58
	v_lshl_add_u64 v[56:57], s[6:7], 1, v[26:27]
	v_lshlrev_b64 v[58:59], 11, v[58:59]
	s_waitcnt lgkmcnt(6)
	v_cvt_pk_bf16_f32 v38, v42, v28
	s_waitcnt lgkmcnt(4)
	v_cvt_pk_bf16_f32 v39, v44, v46
	s_waitcnt lgkmcnt(2)
	v_cvt_pk_bf16_f32 v40, v48, v50
	s_waitcnt lgkmcnt(0)
	v_cvt_pk_bf16_f32 v41, v52, v54
	v_lshl_add_u64 v[58:59], v[56:57], 0, v[58:59]
	v_or_b32_e32 v28, s4, v33
	global_store_dwordx4 v[58:59], v[38:41], off
	s_nop 1
	v_cvt_pk_bf16_f32 v38, v43, v29
	v_ashrrev_i32_e32 v29, 31, v28
	v_cvt_pk_bf16_f32 v39, v45, v47
	v_cvt_pk_bf16_f32 v40, v49, v51
	v_cvt_pk_bf16_f32 v41, v53, v55
	v_lshlrev_b64 v[28:29], 11, v[28:29]
	ds_read2_b32 v[42:43], v32 offset0:49 offset1:57
	ds_read2_b32 v[44:45], v32 offset0:16 offset1:24
	ds_read2_b32 v[46:47], v32 offset0:82 offset1:90
	ds_read2_b32 v[48:49], v32 offset0:115 offset1:123
	ds_read2_b32 v[50:51], v32 offset0:148 offset1:156
	ds_read2_b32 v[52:53], v32 offset0:181 offset1:189
	ds_read2_b32 v[54:55], v32 offset0:214 offset1:222
	ds_read2_b32 v[58:59], v32 offset0:247 offset1:255
	v_lshl_add_u64 v[28:29], v[56:57], 0, v[28:29]
	global_store_dwordx4 v[28:29], v[38:41], off
	v_or_b32_e32 v28, s4, v35
	v_ashrrev_i32_e32 v29, 31, v28
	v_lshlrev_b64 v[28:29], 11, v[28:29]
	s_waitcnt lgkmcnt(6)
	v_cvt_pk_bf16_f32 v38, v44, v42
	s_waitcnt lgkmcnt(4)
	v_cvt_pk_bf16_f32 v39, v46, v48
	s_waitcnt lgkmcnt(2)
	v_cvt_pk_bf16_f32 v40, v50, v52
	s_waitcnt lgkmcnt(0)
	v_cvt_pk_bf16_f32 v41, v54, v58
	v_lshl_add_u64 v[28:29], v[56:57], 0, v[28:29]
	global_store_dwordx4 v[28:29], v[38:41], off
	v_or_b32_e32 v28, s4, v36
	v_ashrrev_i32_e32 v29, 31, v28
	v_lshlrev_b64 v[28:29], 11, v[28:29]
	v_cvt_pk_bf16_f32 v38, v45, v43
	v_cvt_pk_bf16_f32 v39, v47, v49
	v_cvt_pk_bf16_f32 v40, v51, v53
	v_cvt_pk_bf16_f32 v41, v55, v59
	v_lshl_add_u64 v[28:29], v[56:57], 0, v[28:29]
	global_store_dwordx4 v[28:29], v[38:41], off
	s_waitcnt lgkmcnt(0)
	s_branch .LBB0_14

; __device__ __forceinline__ unsigned cvt_pk_bf16(float lo, float hi) { unsigned r; asm volatile("v_cvt_pk_bf16_f32 %0, %1, %2" : "=v"(r) : "v"(lo), "v"(hi)); return r; }
; __device__ __forceinline__ float silu_f(float v) { return v * __builtin_amdgcn_rcpf(1.0f + __builtin_amdgcn_exp2f(-1.4426950408889634f * v)); }
;     __device__ __forceinline__ void operator()(const f32x4 (&acc)[2][2][4][2], const Unit& u, int wr, int wc, int fr, int fq) const {
;     ...
;             for (int m = 0; m < 4; ++m) { bf16_t* rowp = base + (size_t)(row0 + ai * HALF + m * 16) * ldc + col0;
; #pragma unroll
;                 for (int bj = 0; bj < 2; ++bj) { f32x4 v0 = acc[ai][bj][m][0], v1 = acc[ai][bj][m][1];
;                     if (act) {
; #pragma unroll
;                         for (int e = 0; e < 4; ++e) { v0[e] = silu_f(v0[e]); v1[e] = silu_f(v1[e]); } }
;                     u32x4 w; w.x = cvt_pk_bf16(v0[0], v0[1]); w.y = cvt_pk_bf16(v0[2], v0[3]); w.z = cvt_pk_bf16(v1[0], v1[1]); w.w = cvt_pk_bf16(v1[2], v1[3]);
;                     *(u32x4*)(rowp + bj * HALF) = w; } }
.LBB0_127:
	s_lshl_b32 s17, s64, 8
	s_and_b32 s17, s17, 0x300
	s_cmp_eq_u32 s5, 3
	s_cselect_b64 s[72:73], -1, 0
	s_or_b64 s[66:67], s[66:67], s[72:73]
	v_lshl_add_u32 v148, s4, 8, v1
	v_or_b32_e32 v138, s17, v155
	s_and_b64 s[4:5], s[66:67], exec
	s_cselect_b32 s17, 11, 10
	v_lshlrev_b32_e32 v138, 1, v138
	v_ashrrev_i32_e32 v149, 31, v148
	v_lshl_add_u64 v[150:151], s[68:69], 0, v[138:139]
	v_lshlrev_b64 v[152:153], s17, v[148:149]
	v_cvt_pk_bf16_f32 v126, v126, v127
	v_cvt_pk_bf16_f32 v127, v128, v129
	v_cvt_pk_bf16_f32 v128, v122, v123
	v_cndmask_b32_e64 v122, 0, 1, s[70:71]
	v_lshl_add_u64 v[152:153], v[152:153], 1, v[150:151]
	v_cmp_ne_u32_e64 s[4:5], 1, v122
	s_andn2_b64 vcc, exec, s[70:71]
	v_cvt_pk_bf16_f32 v129, v124, v125
	global_store_dwordx4 v[152:153], v[126:129], off sc0 sc1 nt
	s_cbranch_vccnz .LBB0_129
	v_mul_f32_e32 v123, 0xbfb8aa3b, v114
	v_mul_f32_e32 v124, 0xbfb8aa3b, v119
	v_exp_f32_e32 v123, v123
	v_exp_f32_e32 v125, v124
	v_mul_f32_e32 v127, 0xbfb8aa3b, v116
	v_mul_f32_e32 v128, 0xbfb8aa3b, v121
	v_add_f32_e32 v123, 1.0, v123
	v_mul_f32_e32 v122, 0xbfb8aa3b, v118
	v_rcp_f32_e32 v124, v123
	v_add_f32_e32 v123, 1.0, v125
	v_mul_f32_e32 v125, 0xbfb8aa3b, v115
	v_mul_f32_e32 v126, 0xbfb8aa3b, v120
	v_exp_f32_e32 v127, v127
	v_exp_f32_e32 v129, v128
	v_mul_f32_e32 v128, 0xbfb8aa3b, v117
	v_exp_f32_e32 v122, v122
	v_exp_f32_e32 v125, v125
	v_exp_f32_e32 v126, v126
	v_exp_f32_e32 v138, v128
	v_add_f32_e32 v127, 1.0, v127
	v_add_f32_e32 v122, 1.0, v122
	v_add_f32_e32 v125, 1.0, v125
	v_add_f32_e32 v126, 1.0, v126
	v_rcp_f32_e32 v128, v127
	v_add_f32_e32 v127, 1.0, v129
	v_add_f32_e32 v129, 1.0, v138
	v_rcp_f32_e32 v122, v122
	v_rcp_f32_e32 v123, v123
	v_rcp_f32_e32 v126, v126
	v_rcp_f32_e32 v127, v127
	v_rcp_f32_e32 v129, v129
	v_rcp_f32_e32 v125, v125
	v_pk_mul_f32 v[118:119], v[118:119], v[122:123]
	v_pk_mul_f32 v[120:121], v[120:121], v[126:127]
	v_pk_mul_f32 v[116:117], v[116:117], v[128:129]
	v_pk_mul_f32 v[114:115], v[114:115], v[124:125]
.LBB0_129:
	s_and_b64 vcc, exec, s[4:5]
	v_cvt_pk_bf16_f32 v118, v118, v119
	v_cvt_pk_bf16_f32 v119, v120, v121
	v_cvt_pk_bf16_f32 v120, v114, v115
	v_cvt_pk_bf16_f32 v121, v116, v117
	global_store_dwordx4 v[152:153], v[118:121], off offset:256 sc0 sc1 nt
	s_cbranch_vccnz .LBB0_131
	v_mul_f32_e32 v115, 0xbfb8aa3b, v106
	v_mul_f32_e32 v116, 0xbfb8aa3b, v111
	v_exp_f32_e32 v115, v115
	v_exp_f32_e32 v117, v116
	v_mul_f32_e32 v119, 0xbfb8aa3b, v108
	v_mul_f32_e32 v120, 0xbfb8aa3b, v113
	v_add_f32_e32 v115, 1.0, v115
	v_mul_f32_e32 v114, 0xbfb8aa3b, v110
	v_rcp_f32_e32 v116, v115
	v_add_f32_e32 v115, 1.0, v117
	v_mul_f32_e32 v117, 0xbfb8aa3b, v107
	v_mul_f32_e32 v118, 0xbfb8aa3b, v112
	v_exp_f32_e32 v119, v119
	v_exp_f32_e32 v121, v120
	v_mul_f32_e32 v120, 0xbfb8aa3b, v109
	v_exp_f32_e32 v114, v114
	v_exp_f32_e32 v117, v117
	v_exp_f32_e32 v118, v118
	v_exp_f32_e32 v122, v120
	v_add_f32_e32 v119, 1.0, v119
	v_add_f32_e32 v114, 1.0, v114
	v_add_f32_e32 v117, 1.0, v117
	v_add_f32_e32 v118, 1.0, v118
	v_rcp_f32_e32 v120, v119
	v_add_f32_e32 v119, 1.0, v121
	v_add_f32_e32 v121, 1.0, v122
	v_rcp_f32_e32 v114, v114
	v_rcp_f32_e32 v115, v115
	v_rcp_f32_e32 v118, v118
	v_rcp_f32_e32 v119, v119
	v_rcp_f32_e32 v121, v121
	v_rcp_f32_e32 v117, v117
	v_pk_mul_f32 v[110:111], v[110:111], v[114:115]
	v_pk_mul_f32 v[112:113], v[112:113], v[118:119]
	v_pk_mul_f32 v[108:109], v[108:109], v[120:121]
	v_pk_mul_f32 v[106:107], v[106:107], v[116:117]
.LBB0_131:
	v_or_b32_e32 v114, 16, v148
	v_ashrrev_i32_e32 v115, 31, v114
	v_lshlrev_b64 v[114:115], s17, v[114:115]
	v_lshl_add_u64 v[114:115], v[114:115], 1, v[150:151]
	s_and_b64 vcc, exec, s[4:5]
	v_cvt_pk_bf16_f32 v110, v110, v111
	v_cvt_pk_bf16_f32 v111, v112, v113
	v_cvt_pk_bf16_f32 v112, v106, v107
	v_cvt_pk_bf16_f32 v113, v108, v109
	global_store_dwordx4 v[114:115], v[110:113], off sc0 sc1 nt
	s_cbranch_vccnz .LBB0_133
	v_mul_f32_e32 v107, 0xbfb8aa3b, v98
	v_mul_f32_e32 v108, 0xbfb8aa3b, v103
	v_exp_f32_e32 v107, v107
	v_exp_f32_e32 v109, v108
	v_mul_f32_e32 v111, 0xbfb8aa3b, v100
	v_mul_f32_e32 v112, 0xbfb8aa3b, v105
	v_add_f32_e32 v107, 1.0, v107
	v_mul_f32_e32 v106, 0xbfb8aa3b, v102
	v_rcp_f32_e32 v108, v107
	v_add_f32_e32 v107, 1.0, v109
	v_mul_f32_e32 v109, 0xbfb8aa3b, v99
	v_mul_f32_e32 v110, 0xbfb8aa3b, v104
	v_exp_f32_e32 v111, v111
	v_exp_f32_e32 v113, v112
	v_mul_f32_e32 v112, 0xbfb8aa3b, v101
	v_exp_f32_e32 v106, v106
	v_exp_f32_e32 v109, v109
	v_exp_f32_e32 v110, v110
	v_exp_f32_e32 v116, v112
	v_add_f32_e32 v111, 1.0, v111
	v_add_f32_e32 v106, 1.0, v106
	v_add_f32_e32 v109, 1.0, v109
	v_add_f32_e32 v110, 1.0, v110
	v_rcp_f32_e32 v112, v111
	v_add_f32_e32 v111, 1.0, v113
	v_add_f32_e32 v113, 1.0, v116
	v_rcp_f32_e32 v106, v106
	v_rcp_f32_e32 v107, v107
	v_rcp_f32_e32 v110, v110
	v_rcp_f32_e32 v111, v111
	v_rcp_f32_e32 v113, v113
	v_rcp_f32_e32 v109, v109
	v_pk_mul_f32 v[102:103], v[102:103], v[106:107]
	v_pk_mul_f32 v[104:105], v[104:105], v[110:111]
	v_pk_mul_f32 v[100:101], v[100:101], v[112:113]
	v_pk_mul_f32 v[98:99], v[98:99], v[108:109]
; __device__ __forceinline__ unsigned cvt_pk_bf16(float lo, float hi) { unsigned r; asm volatile("v_cvt_pk_bf16_f32 %0, %1, %2" : "=v"(r) : "v"(lo), "v"(hi)); return r; }
; __device__ __forceinline__ float silu_f(float v) { return v * __builtin_amdgcn_rcpf(1.0f + __builtin_amdgcn_exp2f(-1.4426950408889634f * v)); }
;     __device__ __forceinline__ void operator()(const f32x4 (&acc)[2][2][4][2], const Unit& u, int wr, int wc, int fr, int fq) const {
;     ...
;             for (int m = 0; m < 4; ++m) { bf16_t* rowp = base + (size_t)(row0 + ai * HALF + m * 16) * ldc + col0;
; #pragma unroll
;                 for (int bj = 0; bj < 2; ++bj) { f32x4 v0 = acc[ai][bj][m][0], v1 = acc[ai][bj][m][1];
;                     if (act) {
; #pragma unroll
;                         for (int e = 0; e < 4; ++e) { v0[e] = silu_f(v0[e]); v1[e] = silu_f(v1[e]); } }
;                     u32x4 w; w.x = cvt_pk_bf16(v0[0], v0[1]); w.y = cvt_pk_bf16(v0[2], v0[3]); w.z = cvt_pk_bf16(v1[0], v1[1]); w.w = cvt_pk_bf16(v1[2], v1[3]);
;                     *(u32x4*)(rowp + bj * HALF) = w; } }
.LBB0_133:
	s_and_b64 vcc, exec, s[4:5]
	v_cvt_pk_bf16_f32 v102, v102, v103
	v_cvt_pk_bf16_f32 v103, v104, v105
	v_cvt_pk_bf16_f32 v104, v98, v99
	v_cvt_pk_bf16_f32 v105, v100, v101
	global_store_dwordx4 v[114:115], v[102:105], off offset:256 sc0 sc1 nt
	s_cbranch_vccnz .LBB0_135
	v_mul_f32_e32 v99, 0xbfb8aa3b, v90
	v_mul_f32_e32 v100, 0xbfb8aa3b, v95
	v_exp_f32_e32 v99, v99
	v_exp_f32_e32 v101, v100
	v_mul_f32_e32 v103, 0xbfb8aa3b, v92
	v_mul_f32_e32 v104, 0xbfb8aa3b, v97
	v_add_f32_e32 v99, 1.0, v99
	v_mul_f32_e32 v98, 0xbfb8aa3b, v94
	v_rcp_f32_e32 v100, v99
	v_add_f32_e32 v99, 1.0, v101
	v_mul_f32_e32 v101, 0xbfb8aa3b, v91
	v_mul_f32_e32 v102, 0xbfb8aa3b, v96
	v_exp_f32_e32 v103, v103
	v_exp_f32_e32 v105, v104
	v_mul_f32_e32 v104, 0xbfb8aa3b, v93
	v_exp_f32_e32 v98, v98
	v_exp_f32_e32 v101, v101
	v_exp_f32_e32 v102, v102
	v_exp_f32_e32 v106, v104
	v_add_f32_e32 v103, 1.0, v103
	v_add_f32_e32 v98, 1.0, v98
	v_add_f32_e32 v101, 1.0, v101
	v_add_f32_e32 v102, 1.0, v102
	v_rcp_f32_e32 v104, v103
	v_add_f32_e32 v103, 1.0, v105
	v_add_f32_e32 v105, 1.0, v106
	v_rcp_f32_e32 v98, v98
	v_rcp_f32_e32 v99, v99
	v_rcp_f32_e32 v102, v102
	v_rcp_f32_e32 v103, v103
	v_rcp_f32_e32 v105, v105
	v_rcp_f32_e32 v101, v101
	v_pk_mul_f32 v[94:95], v[94:95], v[98:99]
	v_pk_mul_f32 v[96:97], v[96:97], v[102:103]
	v_pk_mul_f32 v[92:93], v[92:93], v[104:105]
	v_pk_mul_f32 v[90:91], v[90:91], v[100:101]
.LBB0_135:
	v_or_b32_e32 v98, 32, v148
	v_ashrrev_i32_e32 v99, 31, v98
	v_lshlrev_b64 v[98:99], s17, v[98:99]
	v_lshl_add_u64 v[98:99], v[98:99], 1, v[150:151]
	s_and_b64 vcc, exec, s[4:5]
	v_cvt_pk_bf16_f32 v94, v94, v95
	v_cvt_pk_bf16_f32 v95, v96, v97
	v_cvt_pk_bf16_f32 v96, v90, v91
	v_cvt_pk_bf16_f32 v97, v92, v93
	global_store_dwordx4 v[98:99], v[94:97], off sc0 sc1 nt
	s_cbranch_vccnz .LBB0_137
	v_mul_f32_e32 v91, 0xbfb8aa3b, v82
	v_mul_f32_e32 v92, 0xbfb8aa3b, v87
	v_exp_f32_e32 v91, v91
	v_exp_f32_e32 v93, v92
	v_mul_f32_e32 v95, 0xbfb8aa3b, v84
	v_mul_f32_e32 v96, 0xbfb8aa3b, v89
	v_add_f32_e32 v91, 1.0, v91
	v_mul_f32_e32 v90, 0xbfb8aa3b, v86
	v_rcp_f32_e32 v92, v91
	v_add_f32_e32 v91, 1.0, v93
	v_mul_f32_e32 v93, 0xbfb8aa3b, v83
	v_mul_f32_e32 v94, 0xbfb8aa3b, v88
	v_exp_f32_e32 v95, v95
	v_exp_f32_e32 v97, v96
	v_mul_f32_e32 v96, 0xbfb8aa3b, v85
	v_exp_f32_e32 v90, v90
	v_exp_f32_e32 v93, v93
	v_exp_f32_e32 v94, v94
	v_exp_f32_e32 v100, v96
	v_add_f32_e32 v95, 1.0, v95
	v_add_f32_e32 v90, 1.0, v90
	v_add_f32_e32 v93, 1.0, v93
	v_add_f32_e32 v94, 1.0, v94
	v_rcp_f32_e32 v96, v95
	v_add_f32_e32 v95, 1.0, v97
	v_add_f32_e32 v97, 1.0, v100
	v_rcp_f32_e32 v90, v90
	v_rcp_f32_e32 v91, v91
	v_rcp_f32_e32 v94, v94
	v_rcp_f32_e32 v95, v95
	v_rcp_f32_e32 v97, v97
	v_rcp_f32_e32 v93, v93
	v_pk_mul_f32 v[86:87], v[86:87], v[90:91]
	v_pk_mul_f32 v[88:89], v[88:89], v[94:95]
	v_pk_mul_f32 v[84:85], v[84:85], v[96:97]
	v_pk_mul_f32 v[82:83], v[82:83], v[92:93]
.LBB0_137:
	s_and_b64 vcc, exec, s[4:5]
	v_cvt_pk_bf16_f32 v86, v86, v87
	v_cvt_pk_bf16_f32 v87, v88, v89
	v_cvt_pk_bf16_f32 v88, v82, v83
	v_cvt_pk_bf16_f32 v89, v84, v85
	global_store_dwordx4 v[98:99], v[86:89], off offset:256 sc0 sc1 nt
	s_cbranch_vccnz .LBB0_139
	v_mul_f32_e32 v83, 0xbfb8aa3b, v74
	v_mul_f32_e32 v84, 0xbfb8aa3b, v79
	v_exp_f32_e32 v83, v83
	v_exp_f32_e32 v85, v84
	v_mul_f32_e32 v87, 0xbfb8aa3b, v76
	v_mul_f32_e32 v88, 0xbfb8aa3b, v81
	v_add_f32_e32 v83, 1.0, v83
	v_mul_f32_e32 v82, 0xbfb8aa3b, v78
	v_rcp_f32_e32 v84, v83
	v_add_f32_e32 v83, 1.0, v85
	v_mul_f32_e32 v85, 0xbfb8aa3b, v75
	v_mul_f32_e32 v86, 0xbfb8aa3b, v80
	v_exp_f32_e32 v87, v87
	v_exp_f32_e32 v89, v88
	v_mul_f32_e32 v88, 0xbfb8aa3b, v77
	v_exp_f32_e32 v82, v82
	v_exp_f32_e32 v85, v85
	v_exp_f32_e32 v86, v86
	v_exp_f32_e32 v90, v88
	v_add_f32_e32 v87, 1.0, v87
	v_add_f32_e32 v82, 1.0, v82
	v_add_f32_e32 v85, 1.0, v85
	v_add_f32_e32 v86, 1.0, v86
	v_rcp_f32_e32 v88, v87
	v_add_f32_e32 v87, 1.0, v89
	v_add_f32_e32 v89, 1.0, v90
	v_rcp_f32_e32 v82, v82
	v_rcp_f32_e32 v83, v83
	v_rcp_f32_e32 v86, v86
	v_rcp_f32_e32 v87, v87
	v_rcp_f32_e32 v89, v89
	v_rcp_f32_e32 v85, v85
	v_pk_mul_f32 v[78:79], v[78:79], v[82:83]
	v_pk_mul_f32 v[80:81], v[80:81], v[86:87]
	v_pk_mul_f32 v[76:77], v[76:77], v[88:89]
	v_pk_mul_f32 v[74:75], v[74:75], v[84:85]
.LBB0_139:
	v_or_b32_e32 v82, 48, v148
	v_ashrrev_i32_e32 v83, 31, v82
	v_lshlrev_b64 v[82:83], s17, v[82:83]
	v_lshl_add_u64 v[82:83], v[82:83], 1, v[150:151]
	s_and_b64 vcc, exec, s[4:5]
	v_cvt_pk_bf16_f32 v78, v78, v79
	v_cvt_pk_bf16_f32 v79, v80, v81
	v_cvt_pk_bf16_f32 v80, v74, v75
	v_cvt_pk_bf16_f32 v81, v76, v77
	global_store_dwordx4 v[82:83], v[78:81], off sc0 sc1 nt
	s_cbranch_vccnz .LBB0_141
	v_mul_f32_e32 v75, 0xbfb8aa3b, v66
	v_mul_f32_e32 v76, 0xbfb8aa3b, v71
	v_exp_f32_e32 v75, v75
	v_exp_f32_e32 v77, v76
	v_mul_f32_e32 v79, 0xbfb8aa3b, v68
	v_mul_f32_e32 v80, 0xbfb8aa3b, v73
	v_add_f32_e32 v75, 1.0, v75
	v_mul_f32_e32 v74, 0xbfb8aa3b, v70
	v_rcp_f32_e32 v76, v75
	v_add_f32_e32 v75, 1.0, v77
	v_mul_f32_e32 v77, 0xbfb8aa3b, v67
	v_mul_f32_e32 v78, 0xbfb8aa3b, v72
	v_exp_f32_e32 v79, v79
	v_exp_f32_e32 v81, v80
	v_mul_f32_e32 v80, 0xbfb8aa3b, v69
	v_exp_f32_e32 v74, v74
	v_exp_f32_e32 v77, v77
	v_exp_f32_e32 v78, v78
	v_exp_f32_e32 v84, v80
	v_add_f32_e32 v79, 1.0, v79
	v_add_f32_e32 v74, 1.0, v74
	v_add_f32_e32 v77, 1.0, v77
	v_add_f32_e32 v78, 1.0, v78
	v_rcp_f32_e32 v80, v79
	v_add_f32_e32 v79, 1.0, v81
	v_add_f32_e32 v81, 1.0, v84
	v_rcp_f32_e32 v74, v74
	v_rcp_f32_e32 v75, v75
	v_rcp_f32_e32 v78, v78
	v_rcp_f32_e32 v79, v79
	v_rcp_f32_e32 v81, v81
	v_rcp_f32_e32 v77, v77
	v_pk_mul_f32 v[70:71], v[70:71], v[74:75]
	v_pk_mul_f32 v[72:73], v[72:73], v[78:79]
	v_pk_mul_f32 v[68:69], v[68:69], v[80:81]
	v_pk_mul_f32 v[66:67], v[66:67], v[76:77]
; __device__ __forceinline__ unsigned cvt_pk_bf16(float lo, float hi) { unsigned r; asm volatile("v_cvt_pk_bf16_f32 %0, %1, %2" : "=v"(r) : "v"(lo), "v"(hi)); return r; }
; __device__ __forceinline__ float silu_f(float v) { return v * __builtin_amdgcn_rcpf(1.0f + __builtin_amdgcn_exp2f(-1.4426950408889634f * v)); }
;     __device__ __forceinline__ void operator()(const f32x4 (&acc)[2][2][4][2], const Unit& u, int wr, int wc, int fr, int fq) const {
;     ...
;             for (int m = 0; m < 4; ++m) { bf16_t* rowp = base + (size_t)(row0 + ai * HALF + m * 16) * ldc + col0;
; #pragma unroll
;                 for (int bj = 0; bj < 2; ++bj) { f32x4 v0 = acc[ai][bj][m][0], v1 = acc[ai][bj][m][1];
;                     if (act) {
; #pragma unroll
;                         for (int e = 0; e < 4; ++e) { v0[e] = silu_f(v0[e]); v1[e] = silu_f(v1[e]); } }
;                     u32x4 w; w.x = cvt_pk_bf16(v0[0], v0[1]); w.y = cvt_pk_bf16(v0[2], v0[3]); w.z = cvt_pk_bf16(v1[0], v1[1]); w.w = cvt_pk_bf16(v1[2], v1[3]);
;                     *(u32x4*)(rowp + bj * HALF) = w; } }
.LBB0_141:
	s_and_b64 vcc, exec, s[4:5]
	v_cvt_pk_bf16_f32 v70, v70, v71
	v_cvt_pk_bf16_f32 v71, v72, v73
	v_cvt_pk_bf16_f32 v72, v66, v67
	v_cvt_pk_bf16_f32 v73, v68, v69
	global_store_dwordx4 v[82:83], v[70:73], off offset:256 sc0 sc1 nt
	s_cbranch_vccnz .LBB0_143
	v_mul_f32_e32 v67, 0xbfb8aa3b, v58
	v_mul_f32_e32 v68, 0xbfb8aa3b, v63
	v_exp_f32_e32 v67, v67
	v_exp_f32_e32 v69, v68
	v_mul_f32_e32 v71, 0xbfb8aa3b, v60
	v_mul_f32_e32 v72, 0xbfb8aa3b, v65
	v_add_f32_e32 v67, 1.0, v67
	v_mul_f32_e32 v66, 0xbfb8aa3b, v62
	v_rcp_f32_e32 v68, v67
	v_add_f32_e32 v67, 1.0, v69
	v_mul_f32_e32 v69, 0xbfb8aa3b, v59
	v_mul_f32_e32 v70, 0xbfb8aa3b, v64
	v_exp_f32_e32 v71, v71
	v_exp_f32_e32 v73, v72
	v_mul_f32_e32 v72, 0xbfb8aa3b, v61
	v_exp_f32_e32 v66, v66
	v_exp_f32_e32 v69, v69
	v_exp_f32_e32 v70, v70
	v_exp_f32_e32 v74, v72
	v_add_f32_e32 v71, 1.0, v71
	v_add_f32_e32 v66, 1.0, v66
	v_add_f32_e32 v69, 1.0, v69
	v_add_f32_e32 v70, 1.0, v70
	v_rcp_f32_e32 v72, v71
	v_add_f32_e32 v71, 1.0, v73
	v_add_f32_e32 v73, 1.0, v74
	v_rcp_f32_e32 v66, v66
	v_rcp_f32_e32 v67, v67
	v_rcp_f32_e32 v70, v70
	v_rcp_f32_e32 v71, v71
	v_rcp_f32_e32 v73, v73
	v_rcp_f32_e32 v69, v69
	v_pk_mul_f32 v[62:63], v[62:63], v[66:67]
	v_pk_mul_f32 v[64:65], v[64:65], v[70:71]
	v_pk_mul_f32 v[60:61], v[60:61], v[72:73]
	v_pk_mul_f32 v[58:59], v[58:59], v[68:69]
.LBB0_143:
	v_add_u32_e32 v66, 0x80, v148
	v_ashrrev_i32_e32 v67, 31, v66
	v_lshlrev_b64 v[66:67], s17, v[66:67]
	v_lshl_add_u64 v[66:67], v[66:67], 1, v[150:151]
	s_and_b64 vcc, exec, s[4:5]
	v_cvt_pk_bf16_f32 v62, v62, v63
	v_cvt_pk_bf16_f32 v63, v64, v65
	v_cvt_pk_bf16_f32 v64, v58, v59
	v_cvt_pk_bf16_f32 v65, v60, v61
	global_store_dwordx4 v[66:67], v[62:65], off sc0 sc1 nt
	s_cbranch_vccnz .LBB0_145
	v_mul_f32_e32 v59, 0xbfb8aa3b, v50
	v_mul_f32_e32 v60, 0xbfb8aa3b, v55
	v_exp_f32_e32 v59, v59
	v_exp_f32_e32 v61, v60
	v_mul_f32_e32 v63, 0xbfb8aa3b, v52
	v_mul_f32_e32 v64, 0xbfb8aa3b, v57
	v_add_f32_e32 v59, 1.0, v59
	v_mul_f32_e32 v58, 0xbfb8aa3b, v54
	v_rcp_f32_e32 v60, v59
	v_add_f32_e32 v59, 1.0, v61
	v_mul_f32_e32 v61, 0xbfb8aa3b, v51
	v_mul_f32_e32 v62, 0xbfb8aa3b, v56
	v_exp_f32_e32 v63, v63
	v_exp_f32_e32 v65, v64
	v_mul_f32_e32 v64, 0xbfb8aa3b, v53
	v_exp_f32_e32 v58, v58
	v_exp_f32_e32 v61, v61
	v_exp_f32_e32 v62, v62
	v_exp_f32_e32 v68, v64
	v_add_f32_e32 v63, 1.0, v63
	v_add_f32_e32 v58, 1.0, v58
	v_add_f32_e32 v61, 1.0, v61
	v_add_f32_e32 v62, 1.0, v62
	v_rcp_f32_e32 v64, v63
	v_add_f32_e32 v63, 1.0, v65
	v_add_f32_e32 v65, 1.0, v68
	v_rcp_f32_e32 v58, v58
	v_rcp_f32_e32 v59, v59
	v_rcp_f32_e32 v62, v62
	v_rcp_f32_e32 v63, v63
	v_rcp_f32_e32 v65, v65
	v_rcp_f32_e32 v61, v61
	v_pk_mul_f32 v[54:55], v[54:55], v[58:59]
	v_pk_mul_f32 v[56:57], v[56:57], v[62:63]
	v_pk_mul_f32 v[52:53], v[52:53], v[64:65]
	v_pk_mul_f32 v[50:51], v[50:51], v[60:61]
.LBB0_145:
	s_and_b64 vcc, exec, s[4:5]
	v_cvt_pk_bf16_f32 v54, v54, v55
	v_cvt_pk_bf16_f32 v55, v56, v57
	v_cvt_pk_bf16_f32 v56, v50, v51
	v_cvt_pk_bf16_f32 v57, v52, v53
	global_store_dwordx4 v[66:67], v[54:57], off offset:256 sc0 sc1 nt
	s_cbranch_vccnz .LBB0_147
	v_mul_f32_e32 v51, 0xbfb8aa3b, v42
	v_mul_f32_e32 v52, 0xbfb8aa3b, v47
	v_exp_f32_e32 v51, v51
	v_exp_f32_e32 v53, v52
	v_mul_f32_e32 v55, 0xbfb8aa3b, v44
	v_mul_f32_e32 v56, 0xbfb8aa3b, v49
	v_add_f32_e32 v51, 1.0, v51
	v_mul_f32_e32 v50, 0xbfb8aa3b, v46
	v_rcp_f32_e32 v52, v51
	v_add_f32_e32 v51, 1.0, v53
	v_mul_f32_e32 v53, 0xbfb8aa3b, v43
	v_mul_f32_e32 v54, 0xbfb8aa3b, v48
	v_exp_f32_e32 v55, v55
	v_exp_f32_e32 v57, v56
	v_mul_f32_e32 v56, 0xbfb8aa3b, v45
	v_exp_f32_e32 v50, v50
	v_exp_f32_e32 v53, v53
	v_exp_f32_e32 v54, v54
	v_exp_f32_e32 v58, v56
	v_add_f32_e32 v55, 1.0, v55
	v_add_f32_e32 v50, 1.0, v50
	v_add_f32_e32 v53, 1.0, v53
	v_add_f32_e32 v54, 1.0, v54
	v_rcp_f32_e32 v56, v55
	v_add_f32_e32 v55, 1.0, v57
	v_add_f32_e32 v57, 1.0, v58
	v_rcp_f32_e32 v50, v50
	v_rcp_f32_e32 v51, v51
	v_rcp_f32_e32 v54, v54
	v_rcp_f32_e32 v55, v55
	v_rcp_f32_e32 v57, v57
	v_rcp_f32_e32 v53, v53
	v_pk_mul_f32 v[46:47], v[46:47], v[50:51]
	v_pk_mul_f32 v[48:49], v[48:49], v[54:55]
	v_pk_mul_f32 v[44:45], v[44:45], v[56:57]
	v_pk_mul_f32 v[42:43], v[42:43], v[52:53]
.LBB0_147:
	v_add_u32_e32 v50, 0x90, v148
	v_ashrrev_i32_e32 v51, 31, v50
	v_lshlrev_b64 v[50:51], s17, v[50:51]
	v_lshl_add_u64 v[50:51], v[50:51], 1, v[150:151]
	s_and_b64 vcc, exec, s[4:5]
	v_cvt_pk_bf16_f32 v46, v46, v47
	v_cvt_pk_bf16_f32 v47, v48, v49
	v_cvt_pk_bf16_f32 v48, v42, v43
	v_cvt_pk_bf16_f32 v49, v44, v45
	global_store_dwordx4 v[50:51], v[46:49], off sc0 sc1 nt
	s_cbranch_vccnz .LBB0_149
	v_mul_f32_e32 v43, 0xbfb8aa3b, v34
	v_mul_f32_e32 v44, 0xbfb8aa3b, v39
	v_exp_f32_e32 v43, v43
	v_exp_f32_e32 v45, v44
	v_mul_f32_e32 v47, 0xbfb8aa3b, v36
	v_mul_f32_e32 v48, 0xbfb8aa3b, v41
	v_add_f32_e32 v43, 1.0, v43
	v_mul_f32_e32 v42, 0xbfb8aa3b, v38
	v_rcp_f32_e32 v44, v43
	v_add_f32_e32 v43, 1.0, v45
	v_mul_f32_e32 v45, 0xbfb8aa3b, v35
	v_mul_f32_e32 v46, 0xbfb8aa3b, v40
	v_exp_f32_e32 v47, v47
	v_exp_f32_e32 v49, v48
	v_mul_f32_e32 v48, 0xbfb8aa3b, v37
	v_exp_f32_e32 v42, v42
	v_exp_f32_e32 v45, v45
	v_exp_f32_e32 v46, v46
	v_exp_f32_e32 v52, v48
	v_add_f32_e32 v47, 1.0, v47
	v_add_f32_e32 v42, 1.0, v42
	v_add_f32_e32 v45, 1.0, v45
	v_add_f32_e32 v46, 1.0, v46
	v_rcp_f32_e32 v48, v47
	v_add_f32_e32 v47, 1.0, v49
	v_add_f32_e32 v49, 1.0, v52
	v_rcp_f32_e32 v42, v42
	v_rcp_f32_e32 v43, v43
	v_rcp_f32_e32 v46, v46
	v_rcp_f32_e32 v47, v47
	v_rcp_f32_e32 v49, v49
	v_rcp_f32_e32 v45, v45
	v_pk_mul_f32 v[38:39], v[38:39], v[42:43]
	v_pk_mul_f32 v[40:41], v[40:41], v[46:47]
	v_pk_mul_f32 v[36:37], v[36:37], v[48:49]
	v_pk_mul_f32 v[34:35], v[34:35], v[44:45]
; __device__ __forceinline__ unsigned cvt_pk_bf16(float lo, float hi) { unsigned r; asm volatile("v_cvt_pk_bf16_f32 %0, %1, %2" : "=v"(r) : "v"(lo), "v"(hi)); return r; }
; #define PG8_BAR __builtin_amdgcn_s_barrier()
; __device__ __forceinline__ float silu_f(float v) { return v * __builtin_amdgcn_rcpf(1.0f + __builtin_amdgcn_exp2f(-1.4426950408889634f * v)); }
;     __device__ __forceinline__ void operator()(const f32x4 (&acc)[2][2][4][2], const Unit& u, int wr, int wc, int fr, int fq) const {
;     ...
;             for (int m = 0; m < 4; ++m) { bf16_t* rowp = base + (size_t)(row0 + ai * HALF + m * 16) * ldc + col0;
; #pragma unroll
;                 for (int bj = 0; bj < 2; ++bj) { f32x4 v0 = acc[ai][bj][m][0], v1 = acc[ai][bj][m][1];
;                     if (act) {
; #pragma unroll
;                         for (int e = 0; e < 4; ++e) { v0[e] = silu_f(v0[e]); v1[e] = silu_f(v1[e]); } }
;                     u32x4 w; w.x = cvt_pk_bf16(v0[0], v0[1]); w.y = cvt_pk_bf16(v0[2], v0[3]); w.z = cvt_pk_bf16(v1[0], v1[1]); w.w = cvt_pk_bf16(v1[2], v1[3]);
;                     *(u32x4*)(rowp + bj * HALF) = w; } }
; template <class Epi, class Sched, bool ALIGN_EPI = false, bool SP2 = false>
; __device__ __forceinline__ void gemm_phase(PG8_LAS unsigned char* lds, const Gemm g, const Sched& S, const Epi& E) {
;     ...
;         if constexpr (!Epi::AFTER_DRAIN) { E(acc, cur, wr, wc, fr, fq); S.done(cur); }
;         if (!has_next) break;
; #pragma unroll
;         for (int a = 0; a < 2; ++a)
; #pragma unroll
;             for (int b = 0; b < 2; ++b)
; #pragma unroll
;                 for (int m = 0; m < 4; ++m)
; #pragma unroll
;                     for (int n = 0; n < 2; ++n) acc[a][b][m][n] = (f32x4){0.f, 0.f, 0.f, 0.f};
;         cur = nxt; cA = nA; cB = nB; ++ui;
;         if constexpr (ALIGN_EPI) { if (wr == 1) PG8_BAR; }
.LBB0_149:
	s_and_b64 vcc, exec, s[4:5]
	v_cvt_pk_bf16_f32 v38, v38, v39
	v_cvt_pk_bf16_f32 v39, v40, v41
	v_cvt_pk_bf16_f32 v40, v34, v35
	v_cvt_pk_bf16_f32 v41, v36, v37
	global_store_dwordx4 v[50:51], v[38:41], off offset:256 sc0 sc1 nt
	s_cbranch_vccnz .LBB0_151
	v_mul_f32_e32 v35, 0xbfb8aa3b, v26
	v_mul_f32_e32 v36, 0xbfb8aa3b, v31
	v_exp_f32_e32 v35, v35
	v_exp_f32_e32 v37, v36
	v_mul_f32_e32 v39, 0xbfb8aa3b, v28
	v_mul_f32_e32 v40, 0xbfb8aa3b, v33
	v_add_f32_e32 v35, 1.0, v35
	v_mul_f32_e32 v34, 0xbfb8aa3b, v30
	v_rcp_f32_e32 v36, v35
	v_add_f32_e32 v35, 1.0, v37
	v_mul_f32_e32 v37, 0xbfb8aa3b, v27
	v_mul_f32_e32 v38, 0xbfb8aa3b, v32
	v_exp_f32_e32 v39, v39
	v_exp_f32_e32 v41, v40
	v_mul_f32_e32 v40, 0xbfb8aa3b, v29
	v_exp_f32_e32 v34, v34
	v_exp_f32_e32 v37, v37
	v_exp_f32_e32 v38, v38
	v_exp_f32_e32 v42, v40
	v_add_f32_e32 v39, 1.0, v39
	v_add_f32_e32 v34, 1.0, v34
	v_add_f32_e32 v37, 1.0, v37
	v_add_f32_e32 v38, 1.0, v38
	v_rcp_f32_e32 v40, v39
	v_add_f32_e32 v39, 1.0, v41
	v_add_f32_e32 v41, 1.0, v42
	v_rcp_f32_e32 v34, v34
	v_rcp_f32_e32 v35, v35
	v_rcp_f32_e32 v38, v38
	v_rcp_f32_e32 v39, v39
	v_rcp_f32_e32 v41, v41
	v_rcp_f32_e32 v37, v37
	v_pk_mul_f32 v[30:31], v[30:31], v[34:35]
	v_pk_mul_f32 v[32:33], v[32:33], v[38:39]
	v_pk_mul_f32 v[28:29], v[28:29], v[40:41]
	v_pk_mul_f32 v[26:27], v[26:27], v[36:37]
.LBB0_151:
	v_add_u32_e32 v34, 0xa0, v148
	v_ashrrev_i32_e32 v35, 31, v34
	v_lshlrev_b64 v[34:35], s17, v[34:35]
	v_lshl_add_u64 v[34:35], v[34:35], 1, v[150:151]
	s_and_b64 vcc, exec, s[4:5]
	v_cvt_pk_bf16_f32 v30, v30, v31
	v_cvt_pk_bf16_f32 v31, v32, v33
	v_cvt_pk_bf16_f32 v32, v26, v27
	v_cvt_pk_bf16_f32 v33, v28, v29
	global_store_dwordx4 v[34:35], v[30:33], off sc0 sc1 nt
	s_cbranch_vccnz .LBB0_153
	v_mul_f32_e32 v27, 0xbfb8aa3b, v18
	v_mul_f32_e32 v28, 0xbfb8aa3b, v23
	v_exp_f32_e32 v27, v27
	v_exp_f32_e32 v29, v28
	v_mul_f32_e32 v31, 0xbfb8aa3b, v20
	v_mul_f32_e32 v32, 0xbfb8aa3b, v25
	v_add_f32_e32 v27, 1.0, v27
	v_mul_f32_e32 v26, 0xbfb8aa3b, v22
	v_rcp_f32_e32 v28, v27
	v_add_f32_e32 v27, 1.0, v29
	v_mul_f32_e32 v29, 0xbfb8aa3b, v19
	v_mul_f32_e32 v30, 0xbfb8aa3b, v24
	v_exp_f32_e32 v31, v31
	v_exp_f32_e32 v33, v32
	v_mul_f32_e32 v32, 0xbfb8aa3b, v21
	v_exp_f32_e32 v26, v26
	v_exp_f32_e32 v29, v29
	v_exp_f32_e32 v30, v30
	v_exp_f32_e32 v36, v32
	v_add_f32_e32 v31, 1.0, v31
	v_add_f32_e32 v26, 1.0, v26
	v_add_f32_e32 v29, 1.0, v29
	v_add_f32_e32 v30, 1.0, v30
	v_rcp_f32_e32 v32, v31
	v_add_f32_e32 v31, 1.0, v33
	v_add_f32_e32 v33, 1.0, v36
	v_rcp_f32_e32 v26, v26
	v_rcp_f32_e32 v27, v27
	v_rcp_f32_e32 v30, v30
	v_rcp_f32_e32 v31, v31
	v_rcp_f32_e32 v33, v33
	v_rcp_f32_e32 v29, v29
	v_pk_mul_f32 v[22:23], v[22:23], v[26:27]
	v_pk_mul_f32 v[24:25], v[24:25], v[30:31]
	v_pk_mul_f32 v[20:21], v[20:21], v[32:33]
	v_pk_mul_f32 v[18:19], v[18:19], v[28:29]
.LBB0_153:
	s_and_b64 vcc, exec, s[4:5]
	v_cvt_pk_bf16_f32 v22, v22, v23
	v_cvt_pk_bf16_f32 v23, v24, v25
	v_cvt_pk_bf16_f32 v24, v18, v19
	v_cvt_pk_bf16_f32 v25, v20, v21
	global_store_dwordx4 v[34:35], v[22:25], off offset:256 sc0 sc1 nt
	s_cbranch_vccnz .LBB0_155
	v_mul_f32_e32 v19, 0xbfb8aa3b, v10
	v_mul_f32_e32 v20, 0xbfb8aa3b, v15
	v_exp_f32_e32 v19, v19
	v_exp_f32_e32 v21, v20
	v_mul_f32_e32 v23, 0xbfb8aa3b, v12
	v_mul_f32_e32 v24, 0xbfb8aa3b, v17
	v_add_f32_e32 v19, 1.0, v19
	v_mul_f32_e32 v18, 0xbfb8aa3b, v14
	v_rcp_f32_e32 v20, v19
	v_add_f32_e32 v19, 1.0, v21
	v_mul_f32_e32 v21, 0xbfb8aa3b, v11
	v_mul_f32_e32 v22, 0xbfb8aa3b, v16
	v_exp_f32_e32 v23, v23
	v_exp_f32_e32 v25, v24
	v_mul_f32_e32 v24, 0xbfb8aa3b, v13
	v_exp_f32_e32 v18, v18
	v_exp_f32_e32 v21, v21
	v_exp_f32_e32 v22, v22
	v_exp_f32_e32 v26, v24
	v_add_f32_e32 v23, 1.0, v23
	v_add_f32_e32 v18, 1.0, v18
	v_add_f32_e32 v21, 1.0, v21
	v_add_f32_e32 v22, 1.0, v22
	v_rcp_f32_e32 v24, v23
	v_add_f32_e32 v23, 1.0, v25
	v_add_f32_e32 v25, 1.0, v26
	v_rcp_f32_e32 v18, v18
	v_rcp_f32_e32 v19, v19
	v_rcp_f32_e32 v22, v22
	v_rcp_f32_e32 v23, v23
	v_rcp_f32_e32 v25, v25
	v_rcp_f32_e32 v21, v21
	v_pk_mul_f32 v[14:15], v[14:15], v[18:19]
	v_pk_mul_f32 v[16:17], v[16:17], v[22:23]
	v_pk_mul_f32 v[12:13], v[12:13], v[24:25]
	v_pk_mul_f32 v[10:11], v[10:11], v[20:21]
.LBB0_155:
	v_add_u32_e32 v18, 0xb0, v148
	v_ashrrev_i32_e32 v19, 31, v18
	v_lshlrev_b64 v[18:19], s17, v[18:19]
	v_lshl_add_u64 v[18:19], v[18:19], 1, v[150:151]
	s_and_b64 vcc, exec, s[4:5]
	v_cvt_pk_bf16_f32 v14, v14, v15
	v_cvt_pk_bf16_f32 v15, v16, v17
	v_cvt_pk_bf16_f32 v16, v10, v11
	v_cvt_pk_bf16_f32 v17, v12, v13
	global_store_dwordx4 v[18:19], v[14:17], off sc0 sc1 nt
	s_cbranch_vccnz .LBB0_157
	v_mul_f32_e32 v11, 0xbfb8aa3b, v2
	v_mul_f32_e32 v12, 0xbfb8aa3b, v7
	v_exp_f32_e32 v11, v11
	v_exp_f32_e32 v13, v12
	v_mul_f32_e32 v15, 0xbfb8aa3b, v4
	v_mul_f32_e32 v16, 0xbfb8aa3b, v9
	v_add_f32_e32 v11, 1.0, v11
	v_mul_f32_e32 v10, 0xbfb8aa3b, v6
	v_rcp_f32_e32 v12, v11
	v_add_f32_e32 v11, 1.0, v13
	v_mul_f32_e32 v13, 0xbfb8aa3b, v3
	v_mul_f32_e32 v14, 0xbfb8aa3b, v8
	v_exp_f32_e32 v15, v15
	v_exp_f32_e32 v17, v16
	v_mul_f32_e32 v16, 0xbfb8aa3b, v5
	v_exp_f32_e32 v10, v10
	v_exp_f32_e32 v13, v13
	v_exp_f32_e32 v14, v14
	v_exp_f32_e32 v20, v16
	v_add_f32_e32 v15, 1.0, v15
	v_add_f32_e32 v10, 1.0, v10
	v_add_f32_e32 v13, 1.0, v13
	v_add_f32_e32 v14, 1.0, v14
	v_rcp_f32_e32 v16, v15
	v_add_f32_e32 v15, 1.0, v17
	v_add_f32_e32 v17, 1.0, v20
	v_rcp_f32_e32 v10, v10
	v_rcp_f32_e32 v11, v11
	v_rcp_f32_e32 v14, v14
	v_rcp_f32_e32 v15, v15
	v_rcp_f32_e32 v17, v17
	v_rcp_f32_e32 v13, v13
	v_pk_mul_f32 v[6:7], v[6:7], v[10:11]
	v_pk_mul_f32 v[8:9], v[8:9], v[14:15]
	v_pk_mul_f32 v[4:5], v[4:5], v[16:17]
	v_pk_mul_f32 v[2:3], v[2:3], v[12:13]
.LBB0_157:
	s_andn2_b64 vcc, exec, s[6:7]
	s_mov_b64 s[4:5], -1
	v_cvt_pk_bf16_f32 v6, v6, v7
	v_cvt_pk_bf16_f32 v7, v8, v9
	v_cvt_pk_bf16_f32 v8, v2, v3
	v_cvt_pk_bf16_f32 v9, v4, v5
	global_store_dwordx4 v[18:19], v[6:9], off offset:256 sc0 sc1 nt
	s_cbranch_vccnz .LBB0_98
	s_andn2_b64 vcc, exec, s[8:9]
	s_cbranch_vccnz .LBB0_97
	s_barrier
	s_branch .LBB0_97
